# first two counted waits of a tile after an epilogue leave the epilogue stores (>=8 per wave) in flight: vmcnt(16) instead of vmcnt(8)
# speedup vs baseline: 1.0245x; 1.0094x over previous
; __global__ void __launch_bounds__(NWAVES * 64, 2) mk_fwd(Args a) {
;     ...
;     for (int l = 0; l < NLAYER; ++l) {
;         unsigned char* wl = ws + WS_W + (size_t)l * W_LAYER;
; #pragma unroll 1
;         for (int rep1 = 0; rep1 < REP_P1; ++rep1) {
;             pg8::Gemm g{XB, (const bf16u*)(wl + WL_IN), NTOK, INW, DMOD}; int bxp = bx; asm volatile("" : "+s"(bxp)); pg8::StaticOrder S; S.init(NTOK, INW, G, bxp);
;     ...
;                 const int nwg5 = (NTOK / 256) * (2 * DFF / 256), rem = nwg5 % G;
;                 const bool light = (rem == 0) || (bxp >= rem);
;                 if (light) { int tc_ = threadIdx.x; asm volatile("" : "+v"(tc_)); const int lnc = tc_ & 63; const int nl = (rem == 0) ? G : G - rem, li = (rem == 0) ? bxp : bxp - rem;
.LBB0_135:
	v_writelane_b32 v255, s72, 2
	s_nop 1
	v_writelane_b32 v255, s73, 3
	s_or_b64 exec, exec, s[2:3]
	s_add_u32 s0, s42, 0x100000
	s_addc_u32 s1, s43, 0
	v_writelane_b32 v255, s0, 4
	v_readlane_b32 s4, v253, 38
	s_mov_b32 s91, 0
	v_writelane_b32 v255, s1, 5
	s_add_u32 s0, s42, 0x200000
	s_addc_u32 s1, s43, 0
	s_add_u32 s82, s42, 0x9e00000
	s_addc_u32 s83, s43, 0
	s_add_u32 s6, s42, 0xbe00000
	v_writelane_b32 v255, s0, 6
	s_addc_u32 s7, s43, 0
	v_mov_b32_e32 v245, 0x358637bd
	v_writelane_b32 v255, s1, 7
	s_add_u32 s0, s42, 0xde00000
	v_writelane_b32 v255, s0, 8
	s_addc_u32 s0, s43, 0
	v_writelane_b32 v255, s0, 9
	s_add_u32 s0, s42, 0xfe00000
	v_writelane_b32 v255, s0, 10
	s_addc_u32 s0, s43, 0
	s_add_u32 s28, s42, 0x11e00000
	s_addc_u32 s29, s43, 0
	s_add_u32 s30, s42, 0x13e00000
	s_addc_u32 s31, s43, 0
	v_writelane_b32 v255, s0, 11
	s_add_u32 s0, s42, 0x17e00000
	s_addc_u32 s1, s43, 0
	v_writelane_b32 v255, s0, 12
	s_movk_i32 s61, 0x2000
	v_mov_b32_e32 v1, 0
	v_writelane_b32 v255, s1, 13
	s_add_u32 s0, s42, 0x19e00000
	s_addc_u32 s1, s43, 0
	s_add_u32 s14, s42, 0x1be00000
	s_addc_u32 s15, s43, 0
	s_add_u32 s86, s42, 0x1de00000
	s_addc_u32 s87, s43, 0
	s_ashr_i32 s79, s80, 31
	v_writelane_b32 v255, s0, 14
	s_cmpk_eq_i32 s80, 0x100
	s_mov_b32 s88, 0x8000
	v_writelane_b32 v255, s1, 15
	s_cselect_b64 s[0:1], -1, 0
	v_writelane_b32 v255, s0, 16
	s_lshl_b32 s89, s80, 2
	s_mov_b32 s27, 0xa000
	v_writelane_b32 v255, s1, 17
	s_abs_i32 s0, s80
	s_waitcnt lgkmcnt(0)
	v_cvt_f32_u32_e32 v0, s0
	s_lshl_b32 s1, s4, 5
	v_writelane_b32 v255, s1, 18
	s_sub_i32 s1, 0, s0
	v_rcp_iflag_f32_e32 v0, v0
	s_mov_b32 s26, 0xc000
	v_mov_b32_e32 v234, 1
	s_movk_i32 s10, 0x3ff
	v_mul_f32_e32 v0, 0x4f7ffffe, v0
	v_cvt_u32_f32_e32 v0, v0
	v_mov_b64_e32 v[236:237], 0x800
	v_mov_b32_e32 v235, 0x3e38aa3b
	v_mov_b32_e32 v248, 0xff800000
	v_readfirstlane_b32 s2, v0
	s_mul_i32 s1, s1, s2
	s_mul_hi_u32 s1, s2, s1
	s_add_i32 s2, s2, s1
	s_mul_hi_u32 s1, s2, 0x580
	s_mul_i32 s1, s1, s0
	s_sub_i32 s1, 0x580, s1
	s_sub_i32 s2, s1, s0
	s_cmp_ge_u32 s1, s0
	s_cselect_b32 s1, s2, s1
	s_sub_i32 s2, s1, s0
	s_cmp_ge_u32 s1, s0
	s_cselect_b32 s5, s2, s1
	s_cmp_eq_u32 s5, 0
	s_cselect_b64 s[2:3], -1, 0
	s_sub_i32 s0, s80, s5
	s_lshl_b32 s0, s0, 3
	v_writelane_b32 v255, s0, 19
	s_lshl_b32 s0, s80, 4
	v_writelane_b32 v255, s0, 20
	s_lshl_b32 s0, s4, 6
	s_lshl_b32 s1, s5, 9
	s_sub_i32 s8, s0, s1
	s_sub_i32 s0, s34, s1
	v_writelane_b32 v255, s0, 21
	s_lshl_b32 s0, s4, 2
	s_lshl_b32 s1, s5, 5
	s_sub_i32 s0, s0, s1
	v_writelane_b32 v255, s0, 22
	s_lshl_b32 s0, s80, 5
	s_sub_i32 s0, s0, s1
	v_writelane_b32 v255, s0, 23
	s_lshl_b32 s0, s4, 7
	s_lshl_b32 s1, s5, 10
	s_sub_i32 s0, s0, s1
	s_add_i32 s0, s0, 0xfff92000
	v_writelane_b32 v255, s0, 24
	s_lshl_b32 s0, s80, 10
	s_sub_i32 s0, s0, s1
	v_writelane_b32 v255, s0, 25
	s_lshl_b32 s0, s5, 3
	s_sub_i32 s1, s4, s0
	s_add_i32 s4, s1, 0xfffff240
	v_writelane_b32 v255, s4, 26
	s_mov_b32 s4, s74
	v_writelane_b32 v255, s4, 27
	s_sub_i32 s0, s74, s0
	s_xor_b64 s[2:3], s[2:3], -1
	v_writelane_b32 v255, s5, 28
	v_writelane_b32 v255, s0, 29
	s_add_i32 s0, s8, 0xfffc9000
	v_writelane_b32 v255, s0, 30
	s_add_i32 s0, s1, 0xfffff500
	v_writelane_b32 v255, s0, 31
	s_add_i32 s0, s1, 0xf500
	v_writelane_b32 v255, s0, 32
	v_writelane_b32 v255, s8, 33
	s_add_i32 s0, s8, 0xfffd4000
	v_writelane_b32 v255, s0, 34
	s_lshl_b32 s0, s80, 12
	s_lshl_b32 s1, s5, 12
	v_writelane_b32 v255, s5, 35
	s_sub_i32 s0, s0, s1
	v_writelane_b32 v255, s0, 36
	s_add_i32 s1, 0, 0x23fc0
	v_writelane_b32 v255, s1, 37
	s_add_i32 s1, 0, 0x23fc4
	v_writelane_b32 v255, s1, 38
	v_writelane_b32 v255, s2, 39
	s_lshl_b32 s44, s80, 6
	s_mov_b32 s5, 0x18000
	v_writelane_b32 v255, s3, 40
	v_writelane_b32 v255, s78, 41
	v_writelane_b32 v255, s82, 42
	s_mov_b32 s0, 0x50000
	v_mov_b64_e32 v[230:231], 0xff
	v_writelane_b32 v255, s83, 43
	s_mov_b32 s11, 0x41000000
	s_mov_b64 s[8:9], 0x40000
	s_mov_b64 s[70:71], 0x80
	s_mov_b64 s[62:63], 0x2000
	s_mov_b64 s[94:95], 0x20000
	s_mov_b64 s[72:73], 0x60000
	s_mov_b64 s[74:75], 0x80000
	s_mov_b64 s[66:67], 0xfe40000
	s_mov_b64 s[84:85], 0xfe40080
	s_mov_b32 s92, s91
	v_writelane_b32 v255, s79, 44
	s_barrier
	s_mov_b32 s98, 0
	s_mov_b32 s99, 0
	s_mov_b32 s100, 0
	s_mov_b32 s101, 0
	s_cmpk_lg_i32 s80, 0x100
	s_cbranch_scc1 .Lgb_setup_done
	s_add_u32 s12, s42, 0x318000
	s_addc_u32 s13, s43, 0
	v_and_b32_e32 v2, 63, v244
	v_lshlrev_b32_e32 v3, 4, v2
	global_load_dwordx4 v[4:7], v3, s[12:13] sc1
	v_and_b32_e32 v8, 1, v2
	s_waitcnt vmcnt(0)
	v_readlane_b32 s1, v4, 0
	v_readlane_b32 s2, v5, 0
	v_readlane_b32 s3, v6, 0
	v_readlane_b32 s4, v7, 0
	v_readlane_b32 s16, v4, 1
	v_readlane_b32 s17, v5, 1
	v_readlane_b32 s18, v6, 1
	v_readlane_b32 s19, v7, 1
	v_cmp_eq_u32_e32 vcc, 1, v8
	s_nop 3
	v_mov_b32_e32 v9, s1
	v_mov_b32_e32 v10, s16
	v_cndmask_b32_e32 v9, v9, v10, vcc
	v_mov_b32_e32 v11, s2
	v_mov_b32_e32 v10, s17
	v_cndmask_b32_e32 v11, v11, v10, vcc
	v_mov_b32_e32 v12, s3
	v_mov_b32_e32 v10, s18
	v_cndmask_b32_e32 v12, v12, v10, vcc
	v_mov_b32_e32 v13, s4
	v_mov_b32_e32 v10, s19
	v_cndmask_b32_e32 v13, v13, v10, vcc
	v_xor_b32_e32 v9, v9, v4
	v_xor_b32_e32 v11, v11, v5
	v_xor_b32_e32 v12, v12, v6
	v_xor_b32_e32 v13, v13, v7
	v_or3_b32 v9, v9, v11, v12
	v_or_b32_e32 v9, v9, v13
	v_min_u32_e32 v10, v4, v5
	v_min3_u32 v10, v10, v6, v7
	v_cmp_ne_u32_e32 vcc, 0, v9
	v_cmp_eq_u32_e64 s[2:3], 0, v10
	s_nop 1
	s_or_b64 s[2:3], s[2:3], vcc
	s_cmp_lg_u64 s[2:3], 0
	s_cbranch_scc1 .Lgb_setup_done
	s_mov_b32 s98, 1

; __global__ void __launch_bounds__(NWAVES * 64, 2) mk_fwd(Args a) {
;     ...
;     for (int l = 0; l < NLAYER; ++l) {
;         unsigned char* wl = ws + WS_W + (size_t)l * W_LAYER;
; #pragma unroll 1
;         for (int rep1 = 0; rep1 < REP_P1; ++rep1) {
;             pg8::Gemm g{XB, (const bf16u*)(wl + WL_IN), NTOK, INW, DMOD}; int bxp = bx; asm volatile("" : "+s"(bxp)); pg8::StaticOrder S; S.init(NTOK, INW, G, bxp);
.LBB0_137:
	s_bitset0_b32 s101, 31
	s_or_b64 exec, exec, s[16:17]
	s_cmp_lg_u32 s98, 0
	s_cbranch_scc0 .Lgb_arm_skip
	v_readlane_b32 s100, v253, 56
	v_readlane_b32 s101, v253, 57
	s_nop 3
	s_add_u32 s100, s100, 0x5e80
	s_addc_u32 s101, s101, 0

; #define PG8_STAGE(bufoff, gbase, voff) do { _Pragma("unroll") for (int _i = 0; _i < 2; ++_i) \
;         __builtin_amdgcn_global_load_lds((const unsigned*)((const char*)(gbase) + (voff)[_i]), (PG8_LAS unsigned*)(lds + (bufoff) + ldsw + _i * 8192), 16, 0, 0); } while (0)
; #define PG8_LDA(dst, b, h) do { _Pragma("unroll") for (int m = 0; m < 4; ++m) _Pragma("unroll") for (int k = 0; k < 2; ++k) dst[m][k] = *(const PG8_LAS bf16x8*)(lds + PG8_SA(b, h) + aoff + m * 2048 + k * 1024); } while (0)
; #define PG8_LDB(dst, b, h) do { _Pragma("unroll") for (int n = 0; n < 2; ++n) _Pragma("unroll") for (int k = 0; k < 2; ++k) dst[n][k] = *(const PG8_LAS bf16x8*)(lds + PG8_SB(b, h) + boff + n * 2048 + k * 1024); } while (0)
; #define PG8_MMA(ai, bj, At, Bt) do { __builtin_amdgcn_s_setprio(1); _Pragma("unroll") for (int m = 0; m < 4; ++m) _Pragma("unroll") for (int n = 0; n < 2; ++n) _Pragma("unroll") for (int k = 0; k < 2; ++k) \
;         acc[ai][bj][m][n] = __builtin_amdgcn_mfma_f32_16x16x32_bf16(Bt[n][k], At[m][k], acc[ai][bj][m][n], 0, 0, 0); __builtin_amdgcn_s_setprio(0); } while (0)
; #define PG8_WAIT_V(n) asm volatile("s_waitcnt vmcnt(" #n ")" ::: "memory")
; #define PG8_WAIT_L(n) asm volatile("s_waitcnt lgkmcnt(" #n ")" ::: "memory")
; #define PG8_BAR __builtin_amdgcn_s_barrier()
; #define PG8_SCHED __builtin_amdgcn_sched_barrier(0)
; template <class Epi, class Sched, bool ALIGN_EPI = false, bool SP2 = false, bool SPLITK = false>
; __device__ __forceinline__ void gemm_phase(PG8_LAS unsigned char* lds, const Gemm g, const Sched& S, const Epi& E) {
;     ...
;             PG8_LDB(B0, 0, 0); PG8_LDB(B1, 0, 1); PG8_SCHED; PG8_LDA(At, 0, 0); PG8_STAGE(PG8_SA(1, 1), a1 + hstep, voffA);
;             PG8_WAIT_V(8); PG8_WAIT_L(0); PG8_BAR; PG8_MMA(0, 0, At, B0); PG8_MMA(0, 1, At, B1); PG8_BAR; PG8_SCHED;
;             PG8_LDA(At, 0, 1); PG8_STAGE(PG8_SB(0, 0), b2, voffB); PG8_STAGE(PG8_SB(0, 1), b2 + hstep, voffB); PG8_STAGE(PG8_SA(0, 0), a2, voffA);
;             PG8_WAIT_V(8); PG8_WAIT_L(0); PG8_BAR; PG8_MMA(1, 0, At, B0); PG8_MMA(1, 1, At, B1); PG8_BAR; PG8_SCHED;
.LBB0_165:
	s_add_u32 s35, s54, 0xfffc0080
	s_addc_u32 s43, s55, -1
	s_add_i32 s45, 0, 0x10000
	s_cmp_eq_u32 s25, 12
	s_cselect_b32 s49, s4, s43
	s_cselect_b32 s48, s12, s35
	s_cselect_b32 s47, s21, s24
	s_cselect_b32 s46, s22, s23
	s_add_i32 s35, 0, 0x14000
	v_add_u32_e32 v142, s45, v198
	v_add_u32_e32 v158, s35, v198
	ds_read_b128 v[130:133], v142
	ds_read_b128 v[134:137], v142 offset:1024
	ds_read_b128 v[138:141], v142 offset:2048
	ds_read_b128 v[142:145], v142 offset:3072
	ds_read_b128 v[146:149], v158
	ds_read_b128 v[150:153], v158 offset:1024
	ds_read_b128 v[154:157], v158 offset:2048
	ds_read_b128 v[158:161], v158 offset:3072
	s_add_i32 m0, s51, 0xc000
	ds_read_b128 v[162:165], v199
	ds_read_b128 v[178:181], v199 offset:1024
	ds_read_b128 v[182:185], v199 offset:2048
	ds_read_b128 v[186:189], v199 offset:3072
	ds_read_b128 v[190:193], v199 offset:4096
	ds_read_b128 v[200:203], v199 offset:5120
	ds_read_b128 v[204:207], v199 offset:6144
	ds_read_b128 v[208:211], v199 offset:7168
	global_load_lds_dwordx4 v174, s[54:55]
	s_add_i32 m0, s51, 0xe000
	s_nop 0
	global_load_lds_dwordx4 v176, s[54:55]
	s_bitcmp1_b32 s101, 31
	s_cbranch_scc1 .Lww_165_0a
	s_waitcnt vmcnt(8)
	s_branch .Lww_165_0b
.Lww_165_0a:
	s_waitcnt vmcnt(16)
.Lww_165_0b:
	s_waitcnt lgkmcnt(0)
	s_barrier
	s_setprio 1
	s_waitcnt lgkmcnt(0)
	v_mfma_f32_16x16x32_bf16 v[126:129], v[130:133], v[162:165], v[126:129]
	v_mfma_f32_16x16x32_bf16 v[122:125], v[138:141], v[162:165], v[122:125]
	v_mfma_f32_16x16x32_bf16 v[114:117], v[130:133], v[182:185], v[114:117]
	v_mfma_f32_16x16x32_bf16 v[106:109], v[138:141], v[182:185], v[106:109]
	v_mfma_f32_16x16x32_bf16 v[98:101], v[130:133], v[190:193], v[98:101]
	v_mfma_f32_16x16x32_bf16 v[90:93], v[138:141], v[190:193], v[90:93]
	v_mfma_f32_16x16x32_bf16 v[82:85], v[130:133], v[204:207], v[82:85]
	v_mfma_f32_16x16x32_bf16 v[74:77], v[138:141], v[204:207], v[74:77]
	v_mfma_f32_16x16x32_bf16 v[126:129], v[134:137], v[178:181], v[126:129]
	v_mfma_f32_16x16x32_bf16 v[122:125], v[142:145], v[178:181], v[122:125]
	v_mfma_f32_16x16x32_bf16 v[114:117], v[134:137], v[186:189], v[114:117]
	v_mfma_f32_16x16x32_bf16 v[106:109], v[142:145], v[186:189], v[106:109]
	v_mfma_f32_16x16x32_bf16 v[98:101], v[134:137], v[200:203], v[98:101]
	v_mfma_f32_16x16x32_bf16 v[90:93], v[142:145], v[200:203], v[90:93]
	v_mfma_f32_16x16x32_bf16 v[82:85], v[134:137], v[208:211], v[82:85]
	v_mfma_f32_16x16x32_bf16 v[74:77], v[142:145], v[208:211], v[74:77]
	v_mfma_f32_16x16x32_bf16 v[118:121], v[146:149], v[162:165], v[118:121]
	v_mfma_f32_16x16x32_bf16 v[110:113], v[154:157], v[162:165], v[110:113]
	v_mfma_f32_16x16x32_bf16 v[102:105], v[146:149], v[182:185], v[102:105]
	v_mfma_f32_16x16x32_bf16 v[94:97], v[154:157], v[182:185], v[94:97]
	v_mfma_f32_16x16x32_bf16 v[86:89], v[146:149], v[190:193], v[86:89]
	v_mfma_f32_16x16x32_bf16 v[78:81], v[154:157], v[190:193], v[78:81]
	v_mfma_f32_16x16x32_bf16 v[70:73], v[146:149], v[204:207], v[70:73]
	v_mfma_f32_16x16x32_bf16 v[66:69], v[154:157], v[204:207], v[66:69]
	v_mfma_f32_16x16x32_bf16 v[118:121], v[150:153], v[178:181], v[118:121]
	v_mfma_f32_16x16x32_bf16 v[110:113], v[158:161], v[178:181], v[110:113]
	v_mfma_f32_16x16x32_bf16 v[102:105], v[150:153], v[186:189], v[102:105]
	v_mfma_f32_16x16x32_bf16 v[94:97], v[158:161], v[186:189], v[94:97]
	v_mfma_f32_16x16x32_bf16 v[86:89], v[150:153], v[200:203], v[86:89]
	v_mfma_f32_16x16x32_bf16 v[78:81], v[158:161], v[200:203], v[78:81]
	v_mfma_f32_16x16x32_bf16 v[70:73], v[150:153], v[208:211], v[70:73]
	v_mfma_f32_16x16x32_bf16 v[66:69], v[158:161], v[208:211], v[66:69]
	s_setprio 0
	s_barrier
	s_add_i32 s43, s45, s33
	s_mov_b32 m0, s43
	ds_read_b128 v[162:165], v199 offset:16384
	ds_read_b128 v[178:181], v199 offset:17408
	ds_read_b128 v[182:185], v199 offset:18432
	ds_read_b128 v[186:189], v199 offset:19456
	ds_read_b128 v[190:193], v199 offset:20480
	ds_read_b128 v[200:203], v199 offset:21504
	ds_read_b128 v[204:207], v199 offset:22528
	ds_read_b128 v[208:211], v199 offset:23552
	global_load_lds_dwordx4 v0, s[46:47]
	s_add_i32 m0, s43, 0x2000
	s_add_u32 s76, s46, 0x40000
	s_addc_u32 s77, s47, 0
	s_add_i32 s35, s35, s33
	global_load_lds_dwordx4 v172, s[46:47]
	s_mov_b32 m0, s35
	s_nop 0
	global_load_lds_dwordx4 v0, s[76:77]
	s_add_i32 m0, s35, 0x2000
	s_nop 0
	global_load_lds_dwordx4 v172, s[76:77]
	s_mov_b32 m0, s51
	s_nop 0
	global_load_lds_dwordx4 v168, s[48:49]
	s_mov_b32 m0, s53
	s_nop 0
	global_load_lds_dwordx4 v170, s[48:49]
	s_bitcmp1_b32 s101, 31
	s_cbranch_scc1 .Lww_165_1a
	s_waitcnt vmcnt(8)
	s_branch .Lww_165_1b

; #define PG8_STAGE(bufoff, gbase, voff) do { _Pragma("unroll") for (int _i = 0; _i < 2; ++_i) \
;         __builtin_amdgcn_global_load_lds((const unsigned*)((const char*)(gbase) + (voff)[_i]), (PG8_LAS unsigned*)(lds + (bufoff) + ldsw + _i * 8192), 16, 0, 0); } while (0)
; #define PG8_LDA(dst, b, h) do { _Pragma("unroll") for (int m = 0; m < 4; ++m) _Pragma("unroll") for (int k = 0; k < 2; ++k) dst[m][k] = *(const PG8_LAS bf16x8*)(lds + PG8_SA(b, h) + aoff + m * 2048 + k * 1024); } while (0)
; #define PG8_LDB(dst, b, h) do { _Pragma("unroll") for (int n = 0; n < 2; ++n) _Pragma("unroll") for (int k = 0; k < 2; ++k) dst[n][k] = *(const PG8_LAS bf16x8*)(lds + PG8_SB(b, h) + boff + n * 2048 + k * 1024); } while (0)
; #define PG8_MMA(ai, bj, At, Bt) do { __builtin_amdgcn_s_setprio(1); _Pragma("unroll") for (int m = 0; m < 4; ++m) _Pragma("unroll") for (int n = 0; n < 2; ++n) _Pragma("unroll") for (int k = 0; k < 2; ++k) \
;         acc[ai][bj][m][n] = __builtin_amdgcn_mfma_f32_16x16x32_bf16(Bt[n][k], At[m][k], acc[ai][bj][m][n], 0, 0, 0); __builtin_amdgcn_s_setprio(0); } while (0)
; #define PG8_WAIT_V(n) asm volatile("s_waitcnt vmcnt(" #n ")" ::: "memory")
; #define PG8_WAIT_L(n) asm volatile("s_waitcnt lgkmcnt(" #n ")" ::: "memory")
; #define PG8_BAR __builtin_amdgcn_s_barrier()
; #define PG8_SCHED __builtin_amdgcn_sched_barrier(0)
; template <class Epi, class Sched, bool ALIGN_EPI = false, bool SP2 = false, bool SPLITK = false>
; __device__ __forceinline__ void gemm_phase(PG8_LAS unsigned char* lds, const Gemm g, const Sched& S, const Epi& E) {
;     ...
;             PG8_WAIT_V(8); PG8_WAIT_L(0); PG8_BAR; PG8_MMA(1, 0, At, B0); PG8_MMA(1, 1, At, B1); PG8_BAR; PG8_SCHED;
;             PG8_LDB(B0, 1, 0); PG8_LDB(B1, 1, 1); PG8_SCHED; PG8_LDA(At, 1, 0); PG8_STAGE(PG8_SA(0, 1), a2 + hstep, voffA);
;             PG8_WAIT_V(8); PG8_WAIT_L(0); PG8_BAR; PG8_MMA(0, 0, At, B0); PG8_MMA(0, 1, At, B1); PG8_BAR; PG8_SCHED;
.Lww_165_1b:
	s_bitset0_b32 s101, 31
	s_waitcnt lgkmcnt(0)
	s_barrier
	s_setprio 1
	s_waitcnt lgkmcnt(0)
	v_mfma_f32_16x16x32_bf16 v[62:65], v[130:133], v[162:165], v[62:65]
	v_mfma_f32_16x16x32_bf16 v[58:61], v[138:141], v[162:165], v[58:61]
	v_mfma_f32_16x16x32_bf16 v[50:53], v[130:133], v[182:185], v[50:53]
	v_mfma_f32_16x16x32_bf16 v[42:45], v[138:141], v[182:185], v[42:45]
	v_mfma_f32_16x16x32_bf16 v[34:37], v[130:133], v[190:193], v[34:37]
	v_mfma_f32_16x16x32_bf16 v[26:29], v[138:141], v[190:193], v[26:29]
	v_mfma_f32_16x16x32_bf16 v[18:21], v[130:133], v[204:207], v[18:21]
	v_mfma_f32_16x16x32_bf16 v[10:13], v[138:141], v[204:207], v[10:13]
	v_mfma_f32_16x16x32_bf16 v[62:65], v[134:137], v[178:181], v[62:65]
	v_mfma_f32_16x16x32_bf16 v[58:61], v[142:145], v[178:181], v[58:61]
	v_mfma_f32_16x16x32_bf16 v[50:53], v[134:137], v[186:189], v[50:53]
	v_mfma_f32_16x16x32_bf16 v[42:45], v[142:145], v[186:189], v[42:45]
	v_mfma_f32_16x16x32_bf16 v[34:37], v[134:137], v[200:203], v[34:37]
	v_mfma_f32_16x16x32_bf16 v[26:29], v[142:145], v[200:203], v[26:29]
	v_mfma_f32_16x16x32_bf16 v[18:21], v[134:137], v[208:211], v[18:21]
	v_mfma_f32_16x16x32_bf16 v[10:13], v[142:145], v[208:211], v[10:13]
	v_mfma_f32_16x16x32_bf16 v[54:57], v[146:149], v[162:165], v[54:57]
	v_mfma_f32_16x16x32_bf16 v[46:49], v[154:157], v[162:165], v[46:49]
	v_mfma_f32_16x16x32_bf16 v[38:41], v[146:149], v[182:185], v[38:41]
	v_mfma_f32_16x16x32_bf16 v[30:33], v[154:157], v[182:185], v[30:33]
	v_mfma_f32_16x16x32_bf16 v[22:25], v[146:149], v[190:193], v[22:25]
	v_mfma_f32_16x16x32_bf16 v[14:17], v[154:157], v[190:193], v[14:17]
	v_mfma_f32_16x16x32_bf16 v[6:9], v[146:149], v[204:207], v[6:9]
	v_mfma_f32_16x16x32_bf16 v[2:5], v[154:157], v[204:207], v[2:5]
	v_mfma_f32_16x16x32_bf16 v[54:57], v[150:153], v[178:181], v[54:57]
	v_mfma_f32_16x16x32_bf16 v[46:49], v[158:161], v[178:181], v[46:49]
	v_mfma_f32_16x16x32_bf16 v[38:41], v[150:153], v[186:189], v[38:41]
	v_mfma_f32_16x16x32_bf16 v[30:33], v[158:161], v[186:189], v[30:33]
	v_mfma_f32_16x16x32_bf16 v[22:25], v[150:153], v[200:203], v[22:25]
	v_mfma_f32_16x16x32_bf16 v[14:17], v[158:161], v[200:203], v[14:17]
	v_mfma_f32_16x16x32_bf16 v[6:9], v[150:153], v[208:211], v[6:9]
	v_mfma_f32_16x16x32_bf16 v[2:5], v[158:161], v[208:211], v[2:5]
	s_setprio 0
	s_barrier
	s_add_i32 s35, 0, 0x18000
	s_add_i32 s43, 0, 0x1c000
	v_add_u32_e32 v142, s35, v198
	v_add_u32_e32 v158, s43, v198
	ds_read_b128 v[130:133], v142
	ds_read_b128 v[134:137], v142 offset:1024
	ds_read_b128 v[138:141], v142 offset:2048
	ds_read_b128 v[142:145], v142 offset:3072
	ds_read_b128 v[146:149], v158
	ds_read_b128 v[150:153], v158 offset:1024
	ds_read_b128 v[154:157], v158 offset:2048
	ds_read_b128 v[158:161], v158 offset:3072
	s_add_u32 s48, s48, 0x40000
	s_addc_u32 s49, s49, 0
	s_mov_b32 m0, s56
	ds_read_b128 v[162:165], v199 offset:32768
	ds_read_b128 v[178:181], v199 offset:33792
	ds_read_b128 v[182:185], v199 offset:34816
	ds_read_b128 v[186:189], v199 offset:35840
	ds_read_b128 v[190:193], v199 offset:36864
	ds_read_b128 v[200:203], v199 offset:37888
	ds_read_b128 v[204:207], v199 offset:38912
	ds_read_b128 v[208:211], v199 offset:39936
	global_load_lds_dwordx4 v168, s[48:49]
	s_mov_b32 m0, s57
	s_nop 0
	global_load_lds_dwordx4 v170, s[48:49]
	s_waitcnt vmcnt(8)
	s_waitcnt lgkmcnt(0)
	s_barrier
	s_setprio 1
	s_waitcnt lgkmcnt(0)
	v_mfma_f32_16x16x32_bf16 v[126:129], v[130:133], v[162:165], v[126:129]
	v_mfma_f32_16x16x32_bf16 v[122:125], v[138:141], v[162:165], v[122:125]
	v_mfma_f32_16x16x32_bf16 v[114:117], v[130:133], v[182:185], v[114:117]
	v_mfma_f32_16x16x32_bf16 v[106:109], v[138:141], v[182:185], v[106:109]
	v_mfma_f32_16x16x32_bf16 v[98:101], v[130:133], v[190:193], v[98:101]
	v_mfma_f32_16x16x32_bf16 v[90:93], v[138:141], v[190:193], v[90:93]
	v_mfma_f32_16x16x32_bf16 v[82:85], v[130:133], v[204:207], v[82:85]
	v_mfma_f32_16x16x32_bf16 v[74:77], v[138:141], v[204:207], v[74:77]
	v_mfma_f32_16x16x32_bf16 v[126:129], v[134:137], v[178:181], v[126:129]
	v_mfma_f32_16x16x32_bf16 v[122:125], v[142:145], v[178:181], v[122:125]
	v_mfma_f32_16x16x32_bf16 v[114:117], v[134:137], v[186:189], v[114:117]
	v_mfma_f32_16x16x32_bf16 v[106:109], v[142:145], v[186:189], v[106:109]
	v_mfma_f32_16x16x32_bf16 v[98:101], v[134:137], v[200:203], v[98:101]
	v_mfma_f32_16x16x32_bf16 v[90:93], v[142:145], v[200:203], v[90:93]
	v_mfma_f32_16x16x32_bf16 v[82:85], v[134:137], v[208:211], v[82:85]
	v_mfma_f32_16x16x32_bf16 v[74:77], v[142:145], v[208:211], v[74:77]
	v_mfma_f32_16x16x32_bf16 v[118:121], v[146:149], v[162:165], v[118:121]
	v_mfma_f32_16x16x32_bf16 v[110:113], v[154:157], v[162:165], v[110:113]
	v_mfma_f32_16x16x32_bf16 v[102:105], v[146:149], v[182:185], v[102:105]
	v_mfma_f32_16x16x32_bf16 v[94:97], v[154:157], v[182:185], v[94:97]
	v_mfma_f32_16x16x32_bf16 v[86:89], v[146:149], v[190:193], v[86:89]
	v_mfma_f32_16x16x32_bf16 v[78:81], v[154:157], v[190:193], v[78:81]
	v_mfma_f32_16x16x32_bf16 v[70:73], v[146:149], v[204:207], v[70:73]
	v_mfma_f32_16x16x32_bf16 v[66:69], v[154:157], v[204:207], v[66:69]
	v_mfma_f32_16x16x32_bf16 v[118:121], v[150:153], v[178:181], v[118:121]
	v_mfma_f32_16x16x32_bf16 v[110:113], v[158:161], v[178:181], v[110:113]
	v_mfma_f32_16x16x32_bf16 v[102:105], v[150:153], v[186:189], v[102:105]
	v_mfma_f32_16x16x32_bf16 v[94:97], v[158:161], v[186:189], v[94:97]
	v_mfma_f32_16x16x32_bf16 v[86:89], v[150:153], v[200:203], v[86:89]
	v_mfma_f32_16x16x32_bf16 v[78:81], v[158:161], v[200:203], v[78:81]
	v_mfma_f32_16x16x32_bf16 v[70:73], v[150:153], v[208:211], v[70:73]
	v_mfma_f32_16x16x32_bf16 v[66:69], v[158:161], v[208:211], v[66:69]
	s_setprio 0
	s_barrier
; #define PG8_STAGE(bufoff, gbase, voff) do { _Pragma("unroll") for (int _i = 0; _i < 2; ++_i) \
;         __builtin_amdgcn_global_load_lds((const unsigned*)((const char*)(gbase) + (voff)[_i]), (PG8_LAS unsigned*)(lds + (bufoff) + ldsw + _i * 8192), 16, 0, 0); } while (0)
; #define PG8_LDA(dst, b, h) do { _Pragma("unroll") for (int m = 0; m < 4; ++m) _Pragma("unroll") for (int k = 0; k < 2; ++k) dst[m][k] = *(const PG8_LAS bf16x8*)(lds + PG8_SA(b, h) + aoff + m * 2048 + k * 1024); } while (0)
; #define PG8_MMA(ai, bj, At, Bt) do { __builtin_amdgcn_s_setprio(1); _Pragma("unroll") for (int m = 0; m < 4; ++m) _Pragma("unroll") for (int n = 0; n < 2; ++n) _Pragma("unroll") for (int k = 0; k < 2; ++k) \
;         acc[ai][bj][m][n] = __builtin_amdgcn_mfma_f32_16x16x32_bf16(Bt[n][k], At[m][k], acc[ai][bj][m][n], 0, 0, 0); __builtin_amdgcn_s_setprio(0); } while (0)
; #define PG8_WAIT_V(n) asm volatile("s_waitcnt vmcnt(" #n ")" ::: "memory")
; #define PG8_WAIT_L(n) asm volatile("s_waitcnt lgkmcnt(" #n ")" ::: "memory")
; #define PG8_BAR __builtin_amdgcn_s_barrier()
; #define PG8_SCHED __builtin_amdgcn_sched_barrier(0)
; template <class Epi, class Sched, bool ALIGN_EPI = false, bool SP2 = false, bool SPLITK = false>
; __device__ __forceinline__ void gemm_phase(PG8_LAS unsigned char* lds, const Gemm g, const Sched& S, const Epi& E) {
;     ...
;             PG8_WAIT_V(8); PG8_WAIT_L(0); PG8_BAR; PG8_MMA(0, 0, At, B0); PG8_MMA(0, 1, At, B1); PG8_BAR; PG8_SCHED;
;             PG8_LDA(At, 1, 1); PG8_STAGE(PG8_SB(1, 0), b3, voffB); PG8_STAGE(PG8_SB(1, 1), b3 + hstep, voffB); PG8_STAGE(PG8_SA(1, 0), a3, voffA);
;             PG8_WAIT_V(8); PG8_WAIT_L(0); PG8_BAR; PG8_MMA(1, 0, At, B0); PG8_MMA(1, 1, At, B1); PG8_BAR; PG8_SCHED;
;     ...
;         if constexpr (ALIGN_EPI) { if (wr == 0) PG8_BAR; }
	s_add_i32 s35, s35, s33
	s_add_u32 s46, s46, 0x80
	s_addc_u32 s47, s47, 0
	s_mov_b32 m0, s35
	ds_read_b128 v[162:165], v199 offset:49152
	ds_read_b128 v[178:181], v199 offset:50176
	ds_read_b128 v[182:185], v199 offset:51200
	ds_read_b128 v[186:189], v199 offset:52224
	ds_read_b128 v[190:193], v199 offset:53248
	ds_read_b128 v[200:203], v199 offset:54272
	ds_read_b128 v[204:207], v199 offset:55296
	ds_read_b128 v[208:211], v199 offset:56320
	global_load_lds_dwordx4 v0, s[46:47]
	s_add_i32 m0, s35, 0x2000
	s_add_i32 s35, s43, s33
	global_load_lds_dwordx4 v172, s[46:47]
	s_add_u32 s46, s46, 0x40000
	s_addc_u32 s47, s47, 0
	s_mov_b32 m0, s35
	s_nop 0
	global_load_lds_dwordx4 v0, s[46:47]
	s_add_i32 m0, s35, 0x2000
	s_nop 0
	global_load_lds_dwordx4 v172, s[46:47]
	s_sub_u32 s76, s48, 0x3ff80
	s_subb_u32 s77, s49, 0
	s_mov_b32 m0, s58
	s_nop 0
	global_load_lds_dwordx4 v168, s[76:77]
	s_mov_b32 m0, s59
	s_nop 0
	global_load_lds_dwordx4 v170, s[76:77]
	s_waitcnt vmcnt(8)
	s_waitcnt lgkmcnt(0)
	s_barrier
	s_setprio 1
	s_waitcnt lgkmcnt(0)
	v_mfma_f32_16x16x32_bf16 v[62:65], v[130:133], v[162:165], v[62:65]
	v_mfma_f32_16x16x32_bf16 v[58:61], v[138:141], v[162:165], v[58:61]
	v_mfma_f32_16x16x32_bf16 v[50:53], v[130:133], v[182:185], v[50:53]
	v_mfma_f32_16x16x32_bf16 v[42:45], v[138:141], v[182:185], v[42:45]
	v_mfma_f32_16x16x32_bf16 v[34:37], v[130:133], v[190:193], v[34:37]
	v_mfma_f32_16x16x32_bf16 v[26:29], v[138:141], v[190:193], v[26:29]
	v_mfma_f32_16x16x32_bf16 v[18:21], v[130:133], v[204:207], v[18:21]
	v_mfma_f32_16x16x32_bf16 v[10:13], v[138:141], v[204:207], v[10:13]
	v_mfma_f32_16x16x32_bf16 v[62:65], v[134:137], v[178:181], v[62:65]
	v_mfma_f32_16x16x32_bf16 v[58:61], v[142:145], v[178:181], v[58:61]
	v_mfma_f32_16x16x32_bf16 v[50:53], v[134:137], v[186:189], v[50:53]
	v_mfma_f32_16x16x32_bf16 v[42:45], v[142:145], v[186:189], v[42:45]
	v_mfma_f32_16x16x32_bf16 v[34:37], v[134:137], v[200:203], v[34:37]
	v_mfma_f32_16x16x32_bf16 v[26:29], v[142:145], v[200:203], v[26:29]
	v_mfma_f32_16x16x32_bf16 v[18:21], v[134:137], v[208:211], v[18:21]
	v_mfma_f32_16x16x32_bf16 v[10:13], v[142:145], v[208:211], v[10:13]
	v_mfma_f32_16x16x32_bf16 v[54:57], v[146:149], v[162:165], v[54:57]
	v_mfma_f32_16x16x32_bf16 v[46:49], v[154:157], v[162:165], v[46:49]
	v_mfma_f32_16x16x32_bf16 v[38:41], v[146:149], v[182:185], v[38:41]
	v_mfma_f32_16x16x32_bf16 v[30:33], v[154:157], v[182:185], v[30:33]
	v_mfma_f32_16x16x32_bf16 v[22:25], v[146:149], v[190:193], v[22:25]
	v_mfma_f32_16x16x32_bf16 v[14:17], v[154:157], v[190:193], v[14:17]
	v_mfma_f32_16x16x32_bf16 v[6:9], v[146:149], v[204:207], v[6:9]
	v_mfma_f32_16x16x32_bf16 v[2:5], v[154:157], v[204:207], v[2:5]
	v_mfma_f32_16x16x32_bf16 v[54:57], v[150:153], v[178:181], v[54:57]
	v_mfma_f32_16x16x32_bf16 v[46:49], v[158:161], v[178:181], v[46:49]
	v_mfma_f32_16x16x32_bf16 v[38:41], v[150:153], v[186:189], v[38:41]
	v_mfma_f32_16x16x32_bf16 v[30:33], v[158:161], v[186:189], v[30:33]
	v_mfma_f32_16x16x32_bf16 v[22:25], v[150:153], v[200:203], v[22:25]
	v_mfma_f32_16x16x32_bf16 v[14:17], v[158:161], v[200:203], v[14:17]
	v_mfma_f32_16x16x32_bf16 v[6:9], v[150:153], v[208:211], v[6:9]
	v_mfma_f32_16x16x32_bf16 v[2:5], v[158:161], v[208:211], v[2:5]
	s_setprio 0
	s_barrier
	s_add_i32 s25, s25, 2
	s_add_u32 s54, s54, 0x100
	s_addc_u32 s55, s55, 0
	s_add_u32 s23, s23, 0x100
	s_addc_u32 s24, s24, 0
	s_cmp_gt_u32 s25, 13
	s_cbranch_scc0 .LBB0_165
	s_and_b64 vcc, exec, s[16:17]
	s_cbranch_vccz .LBB0_168
	s_barrier

;     __device__ __forceinline__ void operator()(const f32x4 (&acc)[2][2][4][2], const Unit& u, int wr, int wc, int fr_in, int fq_in) const {
;     ...
;         const int colt = u.pn * BM, sec = colt >> 11, row0 = u.pm * BM + wr * 64 + fr;
;         float rstd[2][4];
;         if (u.pm == pm0) {
.Lgb_p6_skip:
	s_bitset1_b32 s101, 31
	s_lshl_b32 s4, s52, 8
	v_mov_b32_e32 v146, v196
	v_mov_b32_e32 v188, v197
	s_add_i32 s4, s4, s64
	s_mov_b64 s[46:47], -1
	v_add_u32_e32 v178, s4, v146
	s_cmp_eq_u32 s52, s50
	v_ashrrev_i32_e32 v179, 31, v178
	s_cbranch_scc0 .LBB0_173
	s_andn2_b64 vcc, exec, s[46:47]
	s_cbranch_vccz .LBB0_174

; #define PG8_WAIT_V(n) asm volatile("s_waitcnt vmcnt(" #n ")" ::: "memory")
; #define PG8_BAR __builtin_amdgcn_s_barrier()
; template <class Epi, class Sched, bool ALIGN_EPI = false, bool SP2 = false, bool SPLITK = false>
; __device__ __forceinline__ void gemm_phase(PG8_LAS unsigned char* lds, const Gemm g, const Sched& S, const Epi& E) {
;     ...
;     PG8_WAIT_V(0);
;     if constexpr (!ALIGN_EPI) { if (wr == 0) PG8_BAR; }
;     PG8_BAR;
.LBB0_191:
	s_bitset0_b32 s101, 31
	s_waitcnt vmcnt(0)
	v_readlane_b32 s69, v253, 1
	s_barrier

; #define PG8_STAGE(bufoff, gbase, voff) do { _Pragma("unroll") for (int _i = 0; _i < 2; ++_i) \
;         __builtin_amdgcn_global_load_lds((const unsigned*)((const char*)(gbase) + (voff)[_i]), (PG8_LAS unsigned*)(lds + (bufoff) + ldsw + _i * 8192), 16, 0, 0); } while (0)
; #define PG8_LDA(dst, b, h) do { _Pragma("unroll") for (int m = 0; m < 4; ++m) _Pragma("unroll") for (int k = 0; k < 2; ++k) dst[m][k] = *(const PG8_LAS bf16x8*)(lds + PG8_SA(b, h) + aoff + m * 2048 + k * 1024); } while (0)
; #define PG8_LDB(dst, b, h) do { _Pragma("unroll") for (int n = 0; n < 2; ++n) _Pragma("unroll") for (int k = 0; k < 2; ++k) dst[n][k] = *(const PG8_LAS bf16x8*)(lds + PG8_SB(b, h) + boff + n * 2048 + k * 1024); } while (0)
; #define PG8_MMA(ai, bj, At, Bt) do { __builtin_amdgcn_s_setprio(1); _Pragma("unroll") for (int m = 0; m < 4; ++m) _Pragma("unroll") for (int n = 0; n < 2; ++n) _Pragma("unroll") for (int k = 0; k < 2; ++k) \
;         acc[ai][bj][m][n] = __builtin_amdgcn_mfma_f32_16x16x32_bf16(Bt[n][k], At[m][k], acc[ai][bj][m][n], 0, 0, 0); __builtin_amdgcn_s_setprio(0); } while (0)
; #define PG8_WAIT_V(n) asm volatile("s_waitcnt vmcnt(" #n ")" ::: "memory")
; #define PG8_WAIT_L(n) asm volatile("s_waitcnt lgkmcnt(" #n ")" ::: "memory")
; #define PG8_BAR __builtin_amdgcn_s_barrier()
; #define PG8_SCHED __builtin_amdgcn_sched_barrier(0)
; template <class Epi, class Sched, bool ALIGN_EPI = false, bool SP2 = false, bool SPLITK = false>
; __device__ __forceinline__ void gemm_phase(PG8_LAS unsigned char* lds, const Gemm g, const Sched& S, const Epi& E) {
;     ...
;             PG8_LDB(B0, 0, 0); PG8_LDB(B1, 0, 1); PG8_SCHED; PG8_LDA(At, 0, 0); PG8_STAGE(PG8_SA(1, 1), a1 + hstep, voffA);
;             PG8_WAIT_V(8); PG8_WAIT_L(0); PG8_BAR; PG8_MMA(0, 0, At, B0); PG8_MMA(0, 1, At, B1); PG8_BAR; PG8_SCHED;
.LBB0_582:
	s_add_u32 s46, s42, 0xfffc0080
	s_addc_u32 s47, s43, -1
	s_add_i32 s64, 0, 0x10000
	s_cmp_eq_u32 s45, 12
	s_cselect_b32 s49, s4, s47
	s_cselect_b32 s48, s12, s46
	s_cselect_b32 s47, s19, s41
	s_cselect_b32 s46, s21, s25
	s_add_i32 s68, 0, 0x14000
	v_add_u32_e32 v142, s64, v181
	v_add_u32_e32 v168, s68, v181
	ds_read_b128 v[130:133], v142
	ds_read_b128 v[134:137], v142 offset:1024
	ds_read_b128 v[138:141], v142 offset:2048
	ds_read_b128 v[142:145], v142 offset:3072
	ds_read_b128 v[156:159], v168
	ds_read_b128 v[160:163], v168 offset:1024
	ds_read_b128 v[164:167], v168 offset:2048
	ds_read_b128 v[170:173], v168 offset:3072
	s_add_i32 m0, s51, 0xc000
	ds_read_b128 v[176:179], v186
	ds_read_b128 v[182:185], v186 offset:1024
	ds_read_b128 v[188:191], v186 offset:2048
	ds_read_b128 v[192:195], v186 offset:3072
	ds_read_b128 v[196:199], v186 offset:4096
	ds_read_b128 v[200:203], v186 offset:5120
	ds_read_b128 v[204:207], v186 offset:6144
	ds_read_b128 v[208:211], v186 offset:7168
	global_load_lds_dwordx4 v152, s[42:43]
	s_add_i32 m0, s51, 0xe000
	s_nop 0
	global_load_lds_dwordx4 v154, s[42:43]
	s_bitcmp1_b32 s101, 31
	s_cbranch_scc1 .Lww_582_0a
	s_waitcnt vmcnt(8)
	s_branch .Lww_582_0b

; #define PG8_STAGE(bufoff, gbase, voff) do { _Pragma("unroll") for (int _i = 0; _i < 2; ++_i) \
;         __builtin_amdgcn_global_load_lds((const unsigned*)((const char*)(gbase) + (voff)[_i]), (PG8_LAS unsigned*)(lds + (bufoff) + ldsw + _i * 8192), 16, 0, 0); } while (0)
; #define PG8_LDA(dst, b, h) do { _Pragma("unroll") for (int m = 0; m < 4; ++m) _Pragma("unroll") for (int k = 0; k < 2; ++k) dst[m][k] = *(const PG8_LAS bf16x8*)(lds + PG8_SA(b, h) + aoff + m * 2048 + k * 1024); } while (0)
; #define PG8_MMA(ai, bj, At, Bt) do { __builtin_amdgcn_s_setprio(1); _Pragma("unroll") for (int m = 0; m < 4; ++m) _Pragma("unroll") for (int n = 0; n < 2; ++n) _Pragma("unroll") for (int k = 0; k < 2; ++k) \
;         acc[ai][bj][m][n] = __builtin_amdgcn_mfma_f32_16x16x32_bf16(Bt[n][k], At[m][k], acc[ai][bj][m][n], 0, 0, 0); __builtin_amdgcn_s_setprio(0); } while (0)
; #define PG8_WAIT_V(n) asm volatile("s_waitcnt vmcnt(" #n ")" ::: "memory")
; #define PG8_WAIT_L(n) asm volatile("s_waitcnt lgkmcnt(" #n ")" ::: "memory")
; #define PG8_BAR __builtin_amdgcn_s_barrier()
; #define PG8_SCHED __builtin_amdgcn_sched_barrier(0)
; template <class Epi, class Sched, bool ALIGN_EPI = false, bool SP2 = false, bool SPLITK = false>
; __device__ __forceinline__ void gemm_phase(PG8_LAS unsigned char* lds, const Gemm g, const Sched& S, const Epi& E) {
;     ...
;             PG8_WAIT_V(8); PG8_WAIT_L(0); PG8_BAR; PG8_MMA(0, 0, At, B0); PG8_MMA(0, 1, At, B1); PG8_BAR; PG8_SCHED;
;             PG8_LDA(At, 0, 1); PG8_STAGE(PG8_SB(0, 0), b2, voffB); PG8_STAGE(PG8_SB(0, 1), b2 + hstep, voffB); PG8_STAGE(PG8_SA(0, 0), a2, voffA);
;             PG8_WAIT_V(8); PG8_WAIT_L(0); PG8_BAR; PG8_MMA(1, 0, At, B0); PG8_MMA(1, 1, At, B1); PG8_BAR; PG8_SCHED;
.Lww_582_0b:
	s_waitcnt lgkmcnt(0)
	s_barrier
	s_setprio 1
	s_waitcnt lgkmcnt(0)
	v_mfma_f32_16x16x32_bf16 v[126:129], v[130:133], v[176:179], v[126:129]
	v_mfma_f32_16x16x32_bf16 v[118:121], v[138:141], v[176:179], v[118:121]
	v_mfma_f32_16x16x32_bf16 v[110:113], v[130:133], v[188:191], v[110:113]
	v_mfma_f32_16x16x32_bf16 v[102:105], v[138:141], v[188:191], v[102:105]
	v_mfma_f32_16x16x32_bf16 v[94:97], v[130:133], v[196:199], v[94:97]
	v_mfma_f32_16x16x32_bf16 v[86:89], v[138:141], v[196:199], v[86:89]
	v_mfma_f32_16x16x32_bf16 v[78:81], v[130:133], v[204:207], v[78:81]
	v_mfma_f32_16x16x32_bf16 v[70:73], v[138:141], v[204:207], v[70:73]
	v_mfma_f32_16x16x32_bf16 v[126:129], v[134:137], v[182:185], v[126:129]
	v_mfma_f32_16x16x32_bf16 v[118:121], v[142:145], v[182:185], v[118:121]
	v_mfma_f32_16x16x32_bf16 v[110:113], v[134:137], v[192:195], v[110:113]
	v_mfma_f32_16x16x32_bf16 v[102:105], v[142:145], v[192:195], v[102:105]
	v_mfma_f32_16x16x32_bf16 v[94:97], v[134:137], v[200:203], v[94:97]
	v_mfma_f32_16x16x32_bf16 v[86:89], v[142:145], v[200:203], v[86:89]
	v_mfma_f32_16x16x32_bf16 v[78:81], v[134:137], v[208:211], v[78:81]
	v_mfma_f32_16x16x32_bf16 v[70:73], v[142:145], v[208:211], v[70:73]
	v_mfma_f32_16x16x32_bf16 v[122:125], v[156:159], v[176:179], v[122:125]
	v_mfma_f32_16x16x32_bf16 v[114:117], v[164:167], v[176:179], v[114:117]
	v_mfma_f32_16x16x32_bf16 v[106:109], v[156:159], v[188:191], v[106:109]
	v_mfma_f32_16x16x32_bf16 v[98:101], v[164:167], v[188:191], v[98:101]
	v_mfma_f32_16x16x32_bf16 v[90:93], v[156:159], v[196:199], v[90:93]
	v_mfma_f32_16x16x32_bf16 v[82:85], v[164:167], v[196:199], v[82:85]
	v_mfma_f32_16x16x32_bf16 v[74:77], v[156:159], v[204:207], v[74:77]
	v_mfma_f32_16x16x32_bf16 v[66:69], v[164:167], v[204:207], v[66:69]
	v_mfma_f32_16x16x32_bf16 v[122:125], v[160:163], v[182:185], v[122:125]
	v_mfma_f32_16x16x32_bf16 v[114:117], v[170:173], v[182:185], v[114:117]
	v_mfma_f32_16x16x32_bf16 v[106:109], v[160:163], v[192:195], v[106:109]
	v_mfma_f32_16x16x32_bf16 v[98:101], v[170:173], v[192:195], v[98:101]
	v_mfma_f32_16x16x32_bf16 v[90:93], v[160:163], v[200:203], v[90:93]
	v_mfma_f32_16x16x32_bf16 v[82:85], v[170:173], v[200:203], v[82:85]
	v_mfma_f32_16x16x32_bf16 v[74:77], v[160:163], v[208:211], v[74:77]
	v_mfma_f32_16x16x32_bf16 v[66:69], v[170:173], v[208:211], v[66:69]
	s_setprio 0
	s_barrier
	s_add_i32 s64, s64, s23
	s_mov_b32 m0, s64
	ds_read_b128 v[176:179], v186 offset:16384
	ds_read_b128 v[182:185], v186 offset:17408
	ds_read_b128 v[188:191], v186 offset:18432
	ds_read_b128 v[192:195], v186 offset:19456
	ds_read_b128 v[196:199], v186 offset:20480
	ds_read_b128 v[200:203], v186 offset:21504
	ds_read_b128 v[204:207], v186 offset:22528
	ds_read_b128 v[208:211], v186 offset:23552
	global_load_lds_dwordx4 v0, s[46:47]
	s_add_i32 m0, s64, 0x2000
	s_add_u32 s64, s46, 0x40000
	s_addc_u32 s65, s47, 0
	s_add_i32 s68, s68, s23
	global_load_lds_dwordx4 v146, s[46:47]
	s_mov_b32 m0, s68
	s_nop 0
	global_load_lds_dwordx4 v0, s[64:65]
	s_add_i32 m0, s68, 0x2000
	s_nop 0
	global_load_lds_dwordx4 v146, s[64:65]
	s_mov_b32 m0, s51
	s_nop 0
	global_load_lds_dwordx4 v150, s[48:49]
	s_mov_b32 m0, s52
	s_nop 0
	global_load_lds_dwordx4 v148, s[48:49]
	s_bitcmp1_b32 s101, 31
	s_cbranch_scc1 .Lww_582_1a
	s_waitcnt vmcnt(8)
	s_branch .Lww_582_1b

; #define PG8_STAGE(bufoff, gbase, voff) do { _Pragma("unroll") for (int _i = 0; _i < 2; ++_i) \
;         __builtin_amdgcn_global_load_lds((const unsigned*)((const char*)(gbase) + (voff)[_i]), (PG8_LAS unsigned*)(lds + (bufoff) + ldsw + _i * 8192), 16, 0, 0); } while (0)
; #define PG8_LDA(dst, b, h) do { _Pragma("unroll") for (int m = 0; m < 4; ++m) _Pragma("unroll") for (int k = 0; k < 2; ++k) dst[m][k] = *(const PG8_LAS bf16x8*)(lds + PG8_SA(b, h) + aoff + m * 2048 + k * 1024); } while (0)
; #define PG8_LDB(dst, b, h) do { _Pragma("unroll") for (int n = 0; n < 2; ++n) _Pragma("unroll") for (int k = 0; k < 2; ++k) dst[n][k] = *(const PG8_LAS bf16x8*)(lds + PG8_SB(b, h) + boff + n * 2048 + k * 1024); } while (0)
; #define PG8_MMA(ai, bj, At, Bt) do { __builtin_amdgcn_s_setprio(1); _Pragma("unroll") for (int m = 0; m < 4; ++m) _Pragma("unroll") for (int n = 0; n < 2; ++n) _Pragma("unroll") for (int k = 0; k < 2; ++k) \
;         acc[ai][bj][m][n] = __builtin_amdgcn_mfma_f32_16x16x32_bf16(Bt[n][k], At[m][k], acc[ai][bj][m][n], 0, 0, 0); __builtin_amdgcn_s_setprio(0); } while (0)
; #define PG8_WAIT_V(n) asm volatile("s_waitcnt vmcnt(" #n ")" ::: "memory")
; #define PG8_WAIT_L(n) asm volatile("s_waitcnt lgkmcnt(" #n ")" ::: "memory")
; #define PG8_BAR __builtin_amdgcn_s_barrier()
; #define PG8_SCHED __builtin_amdgcn_sched_barrier(0)
; template <class Epi, class Sched, bool ALIGN_EPI = false, bool SP2 = false, bool SPLITK = false>
; __device__ __forceinline__ void gemm_phase(PG8_LAS unsigned char* lds, const Gemm g, const Sched& S, const Epi& E) {
;     ...
;             PG8_WAIT_V(8); PG8_WAIT_L(0); PG8_BAR; PG8_MMA(1, 0, At, B0); PG8_MMA(1, 1, At, B1); PG8_BAR; PG8_SCHED;
;             PG8_LDB(B0, 1, 0); PG8_LDB(B1, 1, 1); PG8_SCHED; PG8_LDA(At, 1, 0); PG8_STAGE(PG8_SA(0, 1), a2 + hstep, voffA);
;             PG8_WAIT_V(8); PG8_WAIT_L(0); PG8_BAR; PG8_MMA(0, 0, At, B0); PG8_MMA(0, 1, At, B1); PG8_BAR; PG8_SCHED;
.Lww_582_1b:
	s_bitset0_b32 s101, 31
	s_waitcnt lgkmcnt(0)
	s_barrier
	s_setprio 1
	s_waitcnt lgkmcnt(0)
	v_mfma_f32_16x16x32_bf16 v[62:65], v[130:133], v[176:179], v[62:65]
	v_mfma_f32_16x16x32_bf16 v[54:57], v[138:141], v[176:179], v[54:57]
	v_mfma_f32_16x16x32_bf16 v[46:49], v[130:133], v[188:191], v[46:49]
	v_mfma_f32_16x16x32_bf16 v[38:41], v[138:141], v[188:191], v[38:41]
	v_mfma_f32_16x16x32_bf16 v[30:33], v[130:133], v[196:199], v[30:33]
	v_mfma_f32_16x16x32_bf16 v[22:25], v[138:141], v[196:199], v[22:25]
	v_mfma_f32_16x16x32_bf16 v[14:17], v[130:133], v[204:207], v[14:17]
	v_mfma_f32_16x16x32_bf16 v[6:9], v[138:141], v[204:207], v[6:9]
	v_mfma_f32_16x16x32_bf16 v[62:65], v[134:137], v[182:185], v[62:65]
	v_mfma_f32_16x16x32_bf16 v[54:57], v[142:145], v[182:185], v[54:57]
	v_mfma_f32_16x16x32_bf16 v[46:49], v[134:137], v[192:195], v[46:49]
	v_mfma_f32_16x16x32_bf16 v[38:41], v[142:145], v[192:195], v[38:41]
	v_mfma_f32_16x16x32_bf16 v[30:33], v[134:137], v[200:203], v[30:33]
	v_mfma_f32_16x16x32_bf16 v[22:25], v[142:145], v[200:203], v[22:25]
	v_mfma_f32_16x16x32_bf16 v[14:17], v[134:137], v[208:211], v[14:17]
	v_mfma_f32_16x16x32_bf16 v[6:9], v[142:145], v[208:211], v[6:9]
	v_mfma_f32_16x16x32_bf16 v[58:61], v[156:159], v[176:179], v[58:61]
	v_mfma_f32_16x16x32_bf16 v[50:53], v[164:167], v[176:179], v[50:53]
	v_mfma_f32_16x16x32_bf16 v[42:45], v[156:159], v[188:191], v[42:45]
	v_mfma_f32_16x16x32_bf16 v[34:37], v[164:167], v[188:191], v[34:37]
	v_mfma_f32_16x16x32_bf16 v[26:29], v[156:159], v[196:199], v[26:29]
	v_mfma_f32_16x16x32_bf16 v[18:21], v[164:167], v[196:199], v[18:21]
	v_mfma_f32_16x16x32_bf16 v[10:13], v[156:159], v[204:207], v[10:13]
	v_mfma_f32_16x16x32_bf16 v[2:5], v[164:167], v[204:207], v[2:5]
	v_mfma_f32_16x16x32_bf16 v[58:61], v[160:163], v[182:185], v[58:61]
	v_mfma_f32_16x16x32_bf16 v[50:53], v[170:173], v[182:185], v[50:53]
	v_mfma_f32_16x16x32_bf16 v[42:45], v[160:163], v[192:195], v[42:45]
	v_mfma_f32_16x16x32_bf16 v[34:37], v[170:173], v[192:195], v[34:37]
	v_mfma_f32_16x16x32_bf16 v[26:29], v[160:163], v[200:203], v[26:29]
	v_mfma_f32_16x16x32_bf16 v[18:21], v[170:173], v[200:203], v[18:21]
	v_mfma_f32_16x16x32_bf16 v[10:13], v[160:163], v[208:211], v[10:13]
	v_mfma_f32_16x16x32_bf16 v[2:5], v[170:173], v[208:211], v[2:5]
	s_setprio 0
	s_barrier
	s_add_i32 s64, 0, 0x18000
	s_add_i32 s65, 0, 0x1c000
	v_add_u32_e32 v142, s64, v181
	v_add_u32_e32 v168, s65, v181
	ds_read_b128 v[130:133], v142
	ds_read_b128 v[134:137], v142 offset:1024
	ds_read_b128 v[138:141], v142 offset:2048
	ds_read_b128 v[142:145], v142 offset:3072
	ds_read_b128 v[156:159], v168
	ds_read_b128 v[160:163], v168 offset:1024
	ds_read_b128 v[164:167], v168 offset:2048
	ds_read_b128 v[170:173], v168 offset:3072
	s_add_u32 vcc_lo, s48, 0x80
	s_addc_u32 vcc_hi, s49, 0
	s_add_u32 s48, s48, 0x40000
	s_addc_u32 s49, s49, 0
	s_mov_b32 m0, s53
	ds_read_b128 v[176:179], v186 offset:32768
	ds_read_b128 v[182:185], v186 offset:33792
	ds_read_b128 v[188:191], v186 offset:34816
	ds_read_b128 v[192:195], v186 offset:35840
	ds_read_b128 v[196:199], v186 offset:36864
	ds_read_b128 v[200:203], v186 offset:37888
	ds_read_b128 v[204:207], v186 offset:38912
	ds_read_b128 v[208:211], v186 offset:39936
	global_load_lds_dwordx4 v150, s[48:49]
	s_mov_b32 m0, s54
	s_nop 0
	global_load_lds_dwordx4 v148, s[48:49]
	s_waitcnt vmcnt(8)
	s_waitcnt lgkmcnt(0)
	s_barrier
	s_setprio 1
	s_waitcnt lgkmcnt(0)
	v_mfma_f32_16x16x32_bf16 v[126:129], v[130:133], v[176:179], v[126:129]
	v_mfma_f32_16x16x32_bf16 v[118:121], v[138:141], v[176:179], v[118:121]
	v_mfma_f32_16x16x32_bf16 v[110:113], v[130:133], v[188:191], v[110:113]
	v_mfma_f32_16x16x32_bf16 v[102:105], v[138:141], v[188:191], v[102:105]
	v_mfma_f32_16x16x32_bf16 v[94:97], v[130:133], v[196:199], v[94:97]
	v_mfma_f32_16x16x32_bf16 v[86:89], v[138:141], v[196:199], v[86:89]
	v_mfma_f32_16x16x32_bf16 v[78:81], v[130:133], v[204:207], v[78:81]
	v_mfma_f32_16x16x32_bf16 v[70:73], v[138:141], v[204:207], v[70:73]
	v_mfma_f32_16x16x32_bf16 v[126:129], v[134:137], v[182:185], v[126:129]
	v_mfma_f32_16x16x32_bf16 v[118:121], v[142:145], v[182:185], v[118:121]
	v_mfma_f32_16x16x32_bf16 v[110:113], v[134:137], v[192:195], v[110:113]
	v_mfma_f32_16x16x32_bf16 v[102:105], v[142:145], v[192:195], v[102:105]
	v_mfma_f32_16x16x32_bf16 v[94:97], v[134:137], v[200:203], v[94:97]
	v_mfma_f32_16x16x32_bf16 v[86:89], v[142:145], v[200:203], v[86:89]
	v_mfma_f32_16x16x32_bf16 v[78:81], v[134:137], v[208:211], v[78:81]
	v_mfma_f32_16x16x32_bf16 v[70:73], v[142:145], v[208:211], v[70:73]
	v_mfma_f32_16x16x32_bf16 v[122:125], v[156:159], v[176:179], v[122:125]
	v_mfma_f32_16x16x32_bf16 v[114:117], v[164:167], v[176:179], v[114:117]
	v_mfma_f32_16x16x32_bf16 v[106:109], v[156:159], v[188:191], v[106:109]
	v_mfma_f32_16x16x32_bf16 v[98:101], v[164:167], v[188:191], v[98:101]
	v_mfma_f32_16x16x32_bf16 v[90:93], v[156:159], v[196:199], v[90:93]
	v_mfma_f32_16x16x32_bf16 v[82:85], v[164:167], v[196:199], v[82:85]
	v_mfma_f32_16x16x32_bf16 v[74:77], v[156:159], v[204:207], v[74:77]
	v_mfma_f32_16x16x32_bf16 v[66:69], v[164:167], v[204:207], v[66:69]
	v_mfma_f32_16x16x32_bf16 v[122:125], v[160:163], v[182:185], v[122:125]
	v_mfma_f32_16x16x32_bf16 v[114:117], v[170:173], v[182:185], v[114:117]
	v_mfma_f32_16x16x32_bf16 v[106:109], v[160:163], v[192:195], v[106:109]
	v_mfma_f32_16x16x32_bf16 v[98:101], v[170:173], v[192:195], v[98:101]
	v_mfma_f32_16x16x32_bf16 v[90:93], v[160:163], v[200:203], v[90:93]
	v_mfma_f32_16x16x32_bf16 v[82:85], v[170:173], v[200:203], v[82:85]
	v_mfma_f32_16x16x32_bf16 v[74:77], v[160:163], v[208:211], v[74:77]
	v_mfma_f32_16x16x32_bf16 v[66:69], v[170:173], v[208:211], v[66:69]
	s_setprio 0
	s_barrier
; #define PG8_STAGE(bufoff, gbase, voff) do { _Pragma("unroll") for (int _i = 0; _i < 2; ++_i) \
;         __builtin_amdgcn_global_load_lds((const unsigned*)((const char*)(gbase) + (voff)[_i]), (PG8_LAS unsigned*)(lds + (bufoff) + ldsw + _i * 8192), 16, 0, 0); } while (0)
; #define PG8_LDA(dst, b, h) do { _Pragma("unroll") for (int m = 0; m < 4; ++m) _Pragma("unroll") for (int k = 0; k < 2; ++k) dst[m][k] = *(const PG8_LAS bf16x8*)(lds + PG8_SA(b, h) + aoff + m * 2048 + k * 1024); } while (0)
; #define PG8_MMA(ai, bj, At, Bt) do { __builtin_amdgcn_s_setprio(1); _Pragma("unroll") for (int m = 0; m < 4; ++m) _Pragma("unroll") for (int n = 0; n < 2; ++n) _Pragma("unroll") for (int k = 0; k < 2; ++k) \
;         acc[ai][bj][m][n] = __builtin_amdgcn_mfma_f32_16x16x32_bf16(Bt[n][k], At[m][k], acc[ai][bj][m][n], 0, 0, 0); __builtin_amdgcn_s_setprio(0); } while (0)
; #define PG8_WAIT_V(n) asm volatile("s_waitcnt vmcnt(" #n ")" ::: "memory")
; #define PG8_WAIT_L(n) asm volatile("s_waitcnt lgkmcnt(" #n ")" ::: "memory")
; #define PG8_BAR __builtin_amdgcn_s_barrier()
; #define PG8_SCHED __builtin_amdgcn_sched_barrier(0)
; template <class Epi, class Sched, bool ALIGN_EPI = false, bool SP2 = false, bool SPLITK = false>
; __device__ __forceinline__ void gemm_phase(PG8_LAS unsigned char* lds, const Gemm g, const Sched& S, const Epi& E) {
;     ...
;             PG8_LDA(At, 1, 1); PG8_STAGE(PG8_SB(1, 0), b3, voffB); PG8_STAGE(PG8_SB(1, 1), b3 + hstep, voffB); PG8_STAGE(PG8_SA(1, 0), a3, voffA);
;             PG8_WAIT_V(8); PG8_WAIT_L(0); PG8_BAR; PG8_MMA(1, 0, At, B0); PG8_MMA(1, 1, At, B1); PG8_BAR; PG8_SCHED;
;     ...
;         if constexpr (ALIGN_EPI) { if (wr == 0) PG8_BAR; }
	s_add_i32 s48, s64, s23
	s_add_u32 s46, s46, 0x80
	s_addc_u32 s47, s47, 0
	s_mov_b32 m0, s48
	ds_read_b128 v[176:179], v186 offset:49152
	ds_read_b128 v[182:185], v186 offset:50176
	ds_read_b128 v[188:191], v186 offset:51200
	ds_read_b128 v[192:195], v186 offset:52224
	ds_read_b128 v[196:199], v186 offset:53248
	ds_read_b128 v[200:203], v186 offset:54272
	ds_read_b128 v[204:207], v186 offset:55296
	ds_read_b128 v[208:211], v186 offset:56320
	global_load_lds_dwordx4 v0, s[46:47]
	s_add_i32 m0, s48, 0x2000
	s_add_i32 s48, s65, s23
	global_load_lds_dwordx4 v146, s[46:47]
	s_add_u32 s46, s46, 0x40000
	s_addc_u32 s47, s47, 0
	s_mov_b32 m0, s48
	s_nop 0
	global_load_lds_dwordx4 v0, s[46:47]
	s_add_i32 m0, s48, 0x2000
	s_nop 0
	global_load_lds_dwordx4 v146, s[46:47]
	s_mov_b32 m0, s55
	s_nop 0
	global_load_lds_dwordx4 v150, vcc
	s_mov_b32 m0, s56
	s_nop 0
	global_load_lds_dwordx4 v148, vcc
	s_waitcnt vmcnt(8)
	s_waitcnt lgkmcnt(0)
	s_barrier
	s_setprio 1
	s_waitcnt lgkmcnt(0)
	v_mfma_f32_16x16x32_bf16 v[62:65], v[130:133], v[176:179], v[62:65]
	v_mfma_f32_16x16x32_bf16 v[54:57], v[138:141], v[176:179], v[54:57]
	v_mfma_f32_16x16x32_bf16 v[46:49], v[130:133], v[188:191], v[46:49]
	v_mfma_f32_16x16x32_bf16 v[38:41], v[138:141], v[188:191], v[38:41]
	v_mfma_f32_16x16x32_bf16 v[30:33], v[130:133], v[196:199], v[30:33]
	v_mfma_f32_16x16x32_bf16 v[22:25], v[138:141], v[196:199], v[22:25]
	v_mfma_f32_16x16x32_bf16 v[14:17], v[130:133], v[204:207], v[14:17]
	v_mfma_f32_16x16x32_bf16 v[6:9], v[138:141], v[204:207], v[6:9]
	v_mfma_f32_16x16x32_bf16 v[62:65], v[134:137], v[182:185], v[62:65]
	v_mfma_f32_16x16x32_bf16 v[54:57], v[142:145], v[182:185], v[54:57]
	v_mfma_f32_16x16x32_bf16 v[46:49], v[134:137], v[192:195], v[46:49]
	v_mfma_f32_16x16x32_bf16 v[38:41], v[142:145], v[192:195], v[38:41]
	v_mfma_f32_16x16x32_bf16 v[30:33], v[134:137], v[200:203], v[30:33]
	v_mfma_f32_16x16x32_bf16 v[22:25], v[142:145], v[200:203], v[22:25]
	v_mfma_f32_16x16x32_bf16 v[14:17], v[134:137], v[208:211], v[14:17]
	v_mfma_f32_16x16x32_bf16 v[6:9], v[142:145], v[208:211], v[6:9]
	v_mfma_f32_16x16x32_bf16 v[58:61], v[156:159], v[176:179], v[58:61]
	v_mfma_f32_16x16x32_bf16 v[50:53], v[164:167], v[176:179], v[50:53]
	v_mfma_f32_16x16x32_bf16 v[42:45], v[156:159], v[188:191], v[42:45]
	v_mfma_f32_16x16x32_bf16 v[34:37], v[164:167], v[188:191], v[34:37]
	v_mfma_f32_16x16x32_bf16 v[26:29], v[156:159], v[196:199], v[26:29]
	v_mfma_f32_16x16x32_bf16 v[18:21], v[164:167], v[196:199], v[18:21]
	v_mfma_f32_16x16x32_bf16 v[10:13], v[156:159], v[204:207], v[10:13]
	v_mfma_f32_16x16x32_bf16 v[2:5], v[164:167], v[204:207], v[2:5]
	v_mfma_f32_16x16x32_bf16 v[58:61], v[160:163], v[182:185], v[58:61]
	v_mfma_f32_16x16x32_bf16 v[50:53], v[170:173], v[182:185], v[50:53]
	v_mfma_f32_16x16x32_bf16 v[42:45], v[160:163], v[192:195], v[42:45]
	v_mfma_f32_16x16x32_bf16 v[34:37], v[170:173], v[192:195], v[34:37]
	v_mfma_f32_16x16x32_bf16 v[26:29], v[160:163], v[200:203], v[26:29]
	v_mfma_f32_16x16x32_bf16 v[18:21], v[170:173], v[200:203], v[18:21]
	v_mfma_f32_16x16x32_bf16 v[10:13], v[160:163], v[208:211], v[10:13]
	v_mfma_f32_16x16x32_bf16 v[2:5], v[170:173], v[208:211], v[2:5]
	s_setprio 0
	s_barrier
	s_add_i32 s45, s45, 2
	s_add_u32 s42, s42, 0x100
	s_addc_u32 s43, s43, 0
	s_add_u32 s25, s25, 0x100
	s_addc_u32 s41, s41, 0
	s_cmp_gt_u32 s45, 13
	s_cbranch_scc0 .LBB0_582
	s_and_b64 vcc, exec, s[16:17]
	s_cbranch_vccz .LBB0_585
	s_barrier

; __device__ __forceinline__ u32x4 pack8(const f32x4 v0, const f32x4 v1) { u32x4 w; w.x = cvt_pk_bf16(v0[0], v0[1]); w.y = cvt_pk_bf16(v0[2], v0[3]); w.z = cvt_pk_bf16(v1[0], v1[1]); w.w = cvt_pk_bf16(v1[2], v1[3]); return w; }
; __device__ __forceinline__ float sigm(float v) { return __builtin_amdgcn_rcpf(1.0f + __expf(-v)); }
;     __device__ __forceinline__ void operator()(const f32x4 (&acc)[2][2][4][2], const Unit& u, int wr, int wc, int fr_in, int fq_in) const {
;     ...
; #pragma unroll
;         for (int ai = 0; ai < 2; ++ai)
; #pragma unroll
;             for (int m = 0; m < 4; ++m) {
;                 f32x4 o[2];
; #pragma unroll
;                 for (int n = 0; n < 2; ++n) {
;                     const f32x4 g = acc[ai][0][m][n] * rstd[ai][m], up = acc[ai][1][m][n] * rstd[ai][m];
; #pragma unroll
;                     for (int e = 0; e < 4; ++e) o[n][e] = g[e] * sigm(g[e]) * up[e];
;                 }
;                 *(u32x4*)(act + (size_t)(row0 + ai * HALF + m * 16) * ldc + u.pn * HALF + wc * 32 + 8 * fq) = pack8(o[0], o[1]);
.LBB0_589:
	s_bitset1_b32 s101, 31
	s_movk_i32 s4, 0x1600
	s_lshl_b32 s40, s24, 8
	v_mul_u32_u24_e32 v131, 0x1600, v182
	s_add_u32 s40, s6, s40
	s_addc_u32 s41, s7, 0
	v_mov_b32_e32 v178, 1.0
	v_mov_b32_e32 v179, 1.0
	s_add_u32 s40, s40, s90
	s_addc_u32 s41, s41, s91
	v_lshl_add_u32 v131, v187, 4, v131
	v_mul_f32_e32 v156, 0xbfb8aa3b, v184
	v_mul_f32_e32 v172, v184, v184
	v_pk_mul_f32 v[158:159], v[126:127], v[156:157] op_sel_hi:[1,0]
	v_pk_mul_f32 v[160:161], v[128:129], v[156:157] op_sel_hi:[1,0]
	v_pk_mul_f32 v[162:163], v[118:119], v[156:157] op_sel_hi:[1,0]
	v_pk_mul_f32 v[166:167], v[120:121], v[156:157] op_sel_hi:[1,0]
	v_exp_f32_e32 v158, v158
	v_exp_f32_e32 v159, v159
	v_pk_mul_f32 v[122:123], v[126:127], v[122:123]
	v_exp_f32_e32 v160, v160
	v_exp_f32_e32 v161, v161
	v_pk_mul_f32 v[124:125], v[128:129], v[124:125]
	v_exp_f32_e32 v162, v162
	v_exp_f32_e32 v163, v163
	v_pk_mul_f32 v[114:115], v[118:119], v[114:115]
	v_exp_f32_e32 v166, v166
	v_exp_f32_e32 v167, v167
	v_pk_mul_f32 v[116:117], v[120:121], v[116:117]
	v_pk_add_f32 v[158:159], v[158:159], v[178:179]
	v_pk_add_f32 v[160:161], v[160:161], v[178:179]
	v_pk_add_f32 v[162:163], v[162:163], v[178:179]
	v_pk_add_f32 v[166:167], v[166:167], v[178:179]
	v_rcp_f32_e32 v158, v158
	v_rcp_f32_e32 v159, v159
	v_pk_mul_f32 v[122:123], v[122:123], v[172:173] op_sel_hi:[1,0]
	v_rcp_f32_e32 v160, v160
	v_rcp_f32_e32 v161, v161
	v_pk_mul_f32 v[124:125], v[124:125], v[172:173] op_sel_hi:[1,0]
	v_rcp_f32_e32 v162, v162
	v_rcp_f32_e32 v163, v163
	v_pk_mul_f32 v[114:115], v[114:115], v[172:173] op_sel_hi:[1,0]
	v_rcp_f32_e32 v166, v166
	v_rcp_f32_e32 v167, v167
	v_pk_mul_f32 v[116:117], v[116:117], v[172:173] op_sel_hi:[1,0]
	v_mul_f32_e32 v156, 0xbfb8aa3b, v180
	v_mul_f32_e32 v172, v180, v180
	v_pk_mul_f32 v[122:123], v[122:123], v[158:159]
	v_pk_mul_f32 v[124:125], v[124:125], v[160:161]
	v_pk_mul_f32 v[114:115], v[114:115], v[162:163]
	v_pk_mul_f32 v[116:117], v[116:117], v[166:167]
	v_cvt_pk_bf16_f32 v132, v122, v123
	v_cvt_pk_bf16_f32 v133, v124, v125
	v_cvt_pk_bf16_f32 v134, v114, v115
	v_cvt_pk_bf16_f32 v135, v116, v117
	s_nop 0
	global_store_dwordx4 v131, v[132:135], s[40:41]
	v_pk_mul_f32 v[158:159], v[110:111], v[156:157] op_sel_hi:[1,0]
	v_pk_mul_f32 v[160:161], v[112:113], v[156:157] op_sel_hi:[1,0]
	v_pk_mul_f32 v[162:163], v[102:103], v[156:157] op_sel_hi:[1,0]
	v_pk_mul_f32 v[166:167], v[104:105], v[156:157] op_sel_hi:[1,0]
	v_add_u32_e32 v131, 0x16000, v131
	v_exp_f32_e32 v158, v158
	v_exp_f32_e32 v159, v159
	v_pk_mul_f32 v[106:107], v[110:111], v[106:107]
	v_exp_f32_e32 v160, v160
	v_exp_f32_e32 v161, v161
	v_pk_mul_f32 v[108:109], v[112:113], v[108:109]
	v_exp_f32_e32 v162, v162
	v_exp_f32_e32 v163, v163
	v_pk_mul_f32 v[98:99], v[102:103], v[98:99]
	v_exp_f32_e32 v166, v166
	v_exp_f32_e32 v167, v167
	v_pk_mul_f32 v[100:101], v[104:105], v[100:101]
	v_pk_add_f32 v[158:159], v[158:159], v[178:179]
	v_pk_add_f32 v[160:161], v[160:161], v[178:179]
	v_pk_add_f32 v[162:163], v[162:163], v[178:179]
	v_pk_add_f32 v[166:167], v[166:167], v[178:179]
	v_rcp_f32_e32 v158, v158
	v_rcp_f32_e32 v159, v159
	v_pk_mul_f32 v[106:107], v[106:107], v[172:173] op_sel_hi:[1,0]
	v_rcp_f32_e32 v160, v160
	v_rcp_f32_e32 v161, v161
	v_pk_mul_f32 v[108:109], v[108:109], v[172:173] op_sel_hi:[1,0]
	v_rcp_f32_e32 v162, v162
	v_rcp_f32_e32 v163, v163
	v_pk_mul_f32 v[98:99], v[98:99], v[172:173] op_sel_hi:[1,0]
	v_rcp_f32_e32 v166, v166
	v_rcp_f32_e32 v167, v167
	v_pk_mul_f32 v[100:101], v[100:101], v[172:173] op_sel_hi:[1,0]
	v_mul_f32_e32 v156, 0xbfb8aa3b, v176
	v_mul_f32_e32 v172, v176, v176
	v_pk_mul_f32 v[106:107], v[106:107], v[158:159]
	v_pk_mul_f32 v[108:109], v[108:109], v[160:161]
	v_pk_mul_f32 v[98:99], v[98:99], v[162:163]
	v_pk_mul_f32 v[100:101], v[100:101], v[166:167]
	v_cvt_pk_bf16_f32 v132, v106, v107
	v_cvt_pk_bf16_f32 v133, v108, v109
	v_cvt_pk_bf16_f32 v134, v98, v99
	v_cvt_pk_bf16_f32 v135, v100, v101
	s_nop 0
	global_store_dwordx4 v131, v[132:135], s[40:41]
	v_pk_mul_f32 v[158:159], v[94:95], v[156:157] op_sel_hi:[1,0]
	v_pk_mul_f32 v[160:161], v[96:97], v[156:157] op_sel_hi:[1,0]
	v_pk_mul_f32 v[162:163], v[86:87], v[156:157] op_sel_hi:[1,0]
	v_pk_mul_f32 v[166:167], v[88:89], v[156:157] op_sel_hi:[1,0]
	v_add_u32_e32 v131, 0x16000, v131
	v_exp_f32_e32 v158, v158
	v_exp_f32_e32 v159, v159
	v_pk_mul_f32 v[90:91], v[94:95], v[90:91]
	v_exp_f32_e32 v160, v160
	v_exp_f32_e32 v161, v161
	v_pk_mul_f32 v[92:93], v[96:97], v[92:93]
	v_exp_f32_e32 v162, v162
	v_exp_f32_e32 v163, v163
	v_pk_mul_f32 v[82:83], v[86:87], v[82:83]
	v_exp_f32_e32 v166, v166
	v_exp_f32_e32 v167, v167
	v_pk_mul_f32 v[84:85], v[88:89], v[84:85]
	v_pk_add_f32 v[158:159], v[158:159], v[178:179]
	v_pk_add_f32 v[160:161], v[160:161], v[178:179]
	v_pk_add_f32 v[162:163], v[162:163], v[178:179]
	v_pk_add_f32 v[166:167], v[166:167], v[178:179]
	v_rcp_f32_e32 v158, v158
	v_rcp_f32_e32 v159, v159
	v_pk_mul_f32 v[90:91], v[90:91], v[172:173] op_sel_hi:[1,0]
	v_rcp_f32_e32 v160, v160
	v_rcp_f32_e32 v161, v161
	v_pk_mul_f32 v[92:93], v[92:93], v[172:173] op_sel_hi:[1,0]
	v_rcp_f32_e32 v162, v162
	v_rcp_f32_e32 v163, v163
	v_pk_mul_f32 v[82:83], v[82:83], v[172:173] op_sel_hi:[1,0]
	v_rcp_f32_e32 v166, v166
	v_rcp_f32_e32 v167, v167
	v_pk_mul_f32 v[84:85], v[84:85], v[172:173] op_sel_hi:[1,0]
	v_mul_f32_e32 v156, 0xbfb8aa3b, v174
	v_mul_f32_e32 v172, v174, v174
	v_pk_mul_f32 v[90:91], v[90:91], v[158:159]
	v_pk_mul_f32 v[92:93], v[92:93], v[160:161]
	v_pk_mul_f32 v[82:83], v[82:83], v[162:163]
	v_pk_mul_f32 v[84:85], v[84:85], v[166:167]
	v_cvt_pk_bf16_f32 v132, v90, v91
	v_cvt_pk_bf16_f32 v133, v92, v93
	v_cvt_pk_bf16_f32 v134, v82, v83
; __device__ __forceinline__ u32x4 pack8(const f32x4 v0, const f32x4 v1) { u32x4 w; w.x = cvt_pk_bf16(v0[0], v0[1]); w.y = cvt_pk_bf16(v0[2], v0[3]); w.z = cvt_pk_bf16(v1[0], v1[1]); w.w = cvt_pk_bf16(v1[2], v1[3]); return w; }
; __device__ __forceinline__ float sigm(float v) { return __builtin_amdgcn_rcpf(1.0f + __expf(-v)); }
;     __device__ __forceinline__ void operator()(const f32x4 (&acc)[2][2][4][2], const Unit& u, int wr, int wc, int fr_in, int fq_in) const {
;     ...
; #pragma unroll
;         for (int ai = 0; ai < 2; ++ai)
; #pragma unroll
;             for (int m = 0; m < 4; ++m) {
;                 f32x4 o[2];
; #pragma unroll
;                 for (int n = 0; n < 2; ++n) {
;                     const f32x4 g = acc[ai][0][m][n] * rstd[ai][m], up = acc[ai][1][m][n] * rstd[ai][m];
; #pragma unroll
;                     for (int e = 0; e < 4; ++e) o[n][e] = g[e] * sigm(g[e]) * up[e];
;                 }
;                 *(u32x4*)(act + (size_t)(row0 + ai * HALF + m * 16) * ldc + u.pn * HALF + wc * 32 + 8 * fq) = pack8(o[0], o[1]);
	v_cvt_pk_bf16_f32 v135, v84, v85
	s_nop 0
	global_store_dwordx4 v131, v[132:135], s[40:41]
	v_pk_mul_f32 v[158:159], v[78:79], v[156:157] op_sel_hi:[1,0]
	v_pk_mul_f32 v[160:161], v[80:81], v[156:157] op_sel_hi:[1,0]
	v_pk_mul_f32 v[162:163], v[70:71], v[156:157] op_sel_hi:[1,0]
	v_pk_mul_f32 v[166:167], v[72:73], v[156:157] op_sel_hi:[1,0]
	v_add_u32_e32 v131, 0x16000, v131
	v_exp_f32_e32 v158, v158
	v_exp_f32_e32 v159, v159
	v_pk_mul_f32 v[74:75], v[78:79], v[74:75]
	v_exp_f32_e32 v160, v160
	v_exp_f32_e32 v161, v161
	v_pk_mul_f32 v[76:77], v[80:81], v[76:77]
	v_exp_f32_e32 v162, v162
	v_exp_f32_e32 v163, v163
	v_pk_mul_f32 v[66:67], v[70:71], v[66:67]
	v_exp_f32_e32 v166, v166
	v_exp_f32_e32 v167, v167
	v_pk_mul_f32 v[68:69], v[72:73], v[68:69]
	v_pk_add_f32 v[158:159], v[158:159], v[178:179]
	v_pk_add_f32 v[160:161], v[160:161], v[178:179]
	v_pk_add_f32 v[162:163], v[162:163], v[178:179]
	v_pk_add_f32 v[166:167], v[166:167], v[178:179]
	v_rcp_f32_e32 v158, v158
	v_rcp_f32_e32 v159, v159
	v_pk_mul_f32 v[74:75], v[74:75], v[172:173] op_sel_hi:[1,0]
	v_rcp_f32_e32 v160, v160
	v_rcp_f32_e32 v161, v161
	v_pk_mul_f32 v[76:77], v[76:77], v[172:173] op_sel_hi:[1,0]
	v_rcp_f32_e32 v162, v162
	v_rcp_f32_e32 v163, v163
	v_pk_mul_f32 v[66:67], v[66:67], v[172:173] op_sel_hi:[1,0]
	v_rcp_f32_e32 v166, v166
	v_rcp_f32_e32 v167, v167
	v_pk_mul_f32 v[68:69], v[68:69], v[172:173] op_sel_hi:[1,0]
	v_mul_f32_e32 v156, 0xbfb8aa3b, v170
	v_mul_f32_e32 v172, v170, v170
	v_pk_mul_f32 v[74:75], v[74:75], v[158:159]
	v_pk_mul_f32 v[76:77], v[76:77], v[160:161]
	v_pk_mul_f32 v[66:67], v[66:67], v[162:163]
	v_pk_mul_f32 v[68:69], v[68:69], v[166:167]
	v_cvt_pk_bf16_f32 v132, v74, v75
	v_cvt_pk_bf16_f32 v133, v76, v77
	v_cvt_pk_bf16_f32 v134, v66, v67
	v_cvt_pk_bf16_f32 v135, v68, v69
	s_nop 0
	global_store_dwordx4 v131, v[132:135], s[40:41]
	v_pk_mul_f32 v[158:159], v[62:63], v[156:157] op_sel_hi:[1,0]
	v_pk_mul_f32 v[160:161], v[64:65], v[156:157] op_sel_hi:[1,0]
	v_pk_mul_f32 v[162:163], v[54:55], v[156:157] op_sel_hi:[1,0]
	v_pk_mul_f32 v[166:167], v[56:57], v[156:157] op_sel_hi:[1,0]
	v_add_u32_e32 v131, 0x6e000, v131
	v_exp_f32_e32 v158, v158
	v_exp_f32_e32 v159, v159
	v_pk_mul_f32 v[58:59], v[62:63], v[58:59]
	v_exp_f32_e32 v160, v160
	v_exp_f32_e32 v161, v161
	v_pk_mul_f32 v[60:61], v[64:65], v[60:61]
	v_exp_f32_e32 v162, v162
	v_exp_f32_e32 v163, v163
	v_pk_mul_f32 v[50:51], v[54:55], v[50:51]
	v_exp_f32_e32 v166, v166
	v_exp_f32_e32 v167, v167
	v_pk_mul_f32 v[52:53], v[56:57], v[52:53]
	v_pk_add_f32 v[158:159], v[158:159], v[178:179]
	v_pk_add_f32 v[160:161], v[160:161], v[178:179]
	v_pk_add_f32 v[162:163], v[162:163], v[178:179]
	v_pk_add_f32 v[166:167], v[166:167], v[178:179]
	v_rcp_f32_e32 v158, v158
	v_rcp_f32_e32 v159, v159
	v_pk_mul_f32 v[58:59], v[58:59], v[172:173] op_sel_hi:[1,0]
	v_rcp_f32_e32 v160, v160
	v_rcp_f32_e32 v161, v161
	v_pk_mul_f32 v[60:61], v[60:61], v[172:173] op_sel_hi:[1,0]
	v_rcp_f32_e32 v162, v162
	v_rcp_f32_e32 v163, v163
	v_pk_mul_f32 v[50:51], v[50:51], v[172:173] op_sel_hi:[1,0]
	v_rcp_f32_e32 v166, v166
	v_rcp_f32_e32 v167, v167
	v_pk_mul_f32 v[52:53], v[52:53], v[172:173] op_sel_hi:[1,0]
	v_mul_f32_e32 v156, 0xbfb8aa3b, v168
	v_mul_f32_e32 v172, v168, v168
	v_pk_mul_f32 v[58:59], v[58:59], v[158:159]
	v_pk_mul_f32 v[60:61], v[60:61], v[160:161]
	v_pk_mul_f32 v[50:51], v[50:51], v[162:163]
	v_pk_mul_f32 v[52:53], v[52:53], v[166:167]
	v_cvt_pk_bf16_f32 v132, v58, v59
	v_cvt_pk_bf16_f32 v133, v60, v61
	v_cvt_pk_bf16_f32 v134, v50, v51
	v_cvt_pk_bf16_f32 v135, v52, v53
	s_nop 0
	global_store_dwordx4 v131, v[132:135], s[40:41]
	v_pk_mul_f32 v[158:159], v[46:47], v[156:157] op_sel_hi:[1,0]
	v_pk_mul_f32 v[160:161], v[48:49], v[156:157] op_sel_hi:[1,0]
	v_pk_mul_f32 v[162:163], v[38:39], v[156:157] op_sel_hi:[1,0]
	v_pk_mul_f32 v[166:167], v[40:41], v[156:157] op_sel_hi:[1,0]
	v_add_u32_e32 v131, 0x16000, v131
	v_exp_f32_e32 v158, v158
	v_exp_f32_e32 v159, v159
	v_pk_mul_f32 v[42:43], v[46:47], v[42:43]
	v_exp_f32_e32 v160, v160
	v_exp_f32_e32 v161, v161
	v_pk_mul_f32 v[44:45], v[48:49], v[44:45]
	v_exp_f32_e32 v162, v162
	v_exp_f32_e32 v163, v163
	v_pk_mul_f32 v[34:35], v[38:39], v[34:35]
	v_exp_f32_e32 v166, v166
	v_exp_f32_e32 v167, v167
	v_pk_mul_f32 v[36:37], v[40:41], v[36:37]
	v_pk_add_f32 v[158:159], v[158:159], v[178:179]
	v_pk_add_f32 v[160:161], v[160:161], v[178:179]
	v_pk_add_f32 v[162:163], v[162:163], v[178:179]
	v_pk_add_f32 v[166:167], v[166:167], v[178:179]
; __device__ __forceinline__ u32x4 pack8(const f32x4 v0, const f32x4 v1) { u32x4 w; w.x = cvt_pk_bf16(v0[0], v0[1]); w.y = cvt_pk_bf16(v0[2], v0[3]); w.z = cvt_pk_bf16(v1[0], v1[1]); w.w = cvt_pk_bf16(v1[2], v1[3]); return w; }
; __device__ __forceinline__ float sigm(float v) { return __builtin_amdgcn_rcpf(1.0f + __expf(-v)); }
;     __device__ __forceinline__ void operator()(const f32x4 (&acc)[2][2][4][2], const Unit& u, int wr, int wc, int fr_in, int fq_in) const {
;     ...
; #pragma unroll
;         for (int ai = 0; ai < 2; ++ai)
; #pragma unroll
;             for (int m = 0; m < 4; ++m) {
;                 f32x4 o[2];
; #pragma unroll
;                 for (int n = 0; n < 2; ++n) {
;                     const f32x4 g = acc[ai][0][m][n] * rstd[ai][m], up = acc[ai][1][m][n] * rstd[ai][m];
; #pragma unroll
;                     for (int e = 0; e < 4; ++e) o[n][e] = g[e] * sigm(g[e]) * up[e];
;                 }
;                 *(u32x4*)(act + (size_t)(row0 + ai * HALF + m * 16) * ldc + u.pn * HALF + wc * 32 + 8 * fq) = pack8(o[0], o[1]);
; template <class Epi, class Sched, bool ALIGN_EPI = false, bool SP2 = false, bool SPLITK = false>
; __device__ __forceinline__ void gemm_phase(PG8_LAS unsigned char* lds, const Gemm g, const Sched& S, const Epi& E) {
;     ...
;         if (!has_next) break;
	v_rcp_f32_e32 v158, v158
	v_rcp_f32_e32 v159, v159
	v_pk_mul_f32 v[42:43], v[42:43], v[172:173] op_sel_hi:[1,0]
	v_rcp_f32_e32 v160, v160
	v_rcp_f32_e32 v161, v161
	v_pk_mul_f32 v[44:45], v[44:45], v[172:173] op_sel_hi:[1,0]
	v_rcp_f32_e32 v162, v162
	v_rcp_f32_e32 v163, v163
	v_pk_mul_f32 v[34:35], v[34:35], v[172:173] op_sel_hi:[1,0]
	v_rcp_f32_e32 v166, v166
	v_rcp_f32_e32 v167, v167
	v_pk_mul_f32 v[36:37], v[36:37], v[172:173] op_sel_hi:[1,0]
	v_mul_f32_e32 v156, 0xbfb8aa3b, v164
	v_mul_f32_e32 v172, v164, v164
	v_pk_mul_f32 v[42:43], v[42:43], v[158:159]
	v_pk_mul_f32 v[44:45], v[44:45], v[160:161]
	v_pk_mul_f32 v[34:35], v[34:35], v[162:163]
	v_pk_mul_f32 v[36:37], v[36:37], v[166:167]
	v_cvt_pk_bf16_f32 v132, v42, v43
	v_cvt_pk_bf16_f32 v133, v44, v45
	v_cvt_pk_bf16_f32 v134, v34, v35
	v_cvt_pk_bf16_f32 v135, v36, v37
	s_nop 0
	global_store_dwordx4 v131, v[132:135], s[40:41]
	v_pk_mul_f32 v[158:159], v[30:31], v[156:157] op_sel_hi:[1,0]
	v_pk_mul_f32 v[160:161], v[32:33], v[156:157] op_sel_hi:[1,0]
	v_pk_mul_f32 v[162:163], v[22:23], v[156:157] op_sel_hi:[1,0]
	v_pk_mul_f32 v[166:167], v[24:25], v[156:157] op_sel_hi:[1,0]
	v_add_u32_e32 v131, 0x16000, v131
	v_exp_f32_e32 v158, v158
	v_exp_f32_e32 v159, v159
	v_pk_mul_f32 v[26:27], v[30:31], v[26:27]
	v_exp_f32_e32 v160, v160
	v_exp_f32_e32 v161, v161
	v_pk_mul_f32 v[28:29], v[32:33], v[28:29]
	v_exp_f32_e32 v162, v162
	v_exp_f32_e32 v163, v163
	v_pk_mul_f32 v[18:19], v[22:23], v[18:19]
	v_exp_f32_e32 v166, v166
	v_exp_f32_e32 v167, v167
	v_pk_mul_f32 v[20:21], v[24:25], v[20:21]
	v_pk_add_f32 v[158:159], v[158:159], v[178:179]
	v_pk_add_f32 v[160:161], v[160:161], v[178:179]
	v_pk_add_f32 v[162:163], v[162:163], v[178:179]
	v_pk_add_f32 v[166:167], v[166:167], v[178:179]
	v_rcp_f32_e32 v158, v158
	v_rcp_f32_e32 v159, v159
	v_pk_mul_f32 v[26:27], v[26:27], v[172:173] op_sel_hi:[1,0]
	v_rcp_f32_e32 v160, v160
	v_rcp_f32_e32 v161, v161
	v_pk_mul_f32 v[28:29], v[28:29], v[172:173] op_sel_hi:[1,0]
	v_rcp_f32_e32 v162, v162
	v_rcp_f32_e32 v163, v163
	v_pk_mul_f32 v[18:19], v[18:19], v[172:173] op_sel_hi:[1,0]
	v_rcp_f32_e32 v166, v166
	v_rcp_f32_e32 v167, v167
	v_pk_mul_f32 v[20:21], v[20:21], v[172:173] op_sel_hi:[1,0]
	v_mul_f32_e32 v156, 0xbfb8aa3b, v130
	v_mul_f32_e32 v172, v130, v130
	v_pk_mul_f32 v[26:27], v[26:27], v[158:159]
	v_pk_mul_f32 v[28:29], v[28:29], v[160:161]
	v_pk_mul_f32 v[18:19], v[18:19], v[162:163]
	v_pk_mul_f32 v[20:21], v[20:21], v[166:167]
	v_cvt_pk_bf16_f32 v132, v26, v27
	v_cvt_pk_bf16_f32 v133, v28, v29
	v_cvt_pk_bf16_f32 v134, v18, v19
	v_cvt_pk_bf16_f32 v135, v20, v21
	s_nop 0
	global_store_dwordx4 v131, v[132:135], s[40:41]
	v_pk_mul_f32 v[158:159], v[14:15], v[156:157] op_sel_hi:[1,0]
	v_pk_mul_f32 v[160:161], v[16:17], v[156:157] op_sel_hi:[1,0]
	v_pk_mul_f32 v[162:163], v[6:7], v[156:157] op_sel_hi:[1,0]
	v_pk_mul_f32 v[166:167], v[8:9], v[156:157] op_sel_hi:[1,0]
	v_add_u32_e32 v131, 0x16000, v131
	v_exp_f32_e32 v158, v158
	v_exp_f32_e32 v159, v159
	v_pk_mul_f32 v[10:11], v[14:15], v[10:11]
	v_exp_f32_e32 v160, v160
	v_exp_f32_e32 v161, v161
	v_pk_mul_f32 v[12:13], v[16:17], v[12:13]
	v_exp_f32_e32 v162, v162
	v_exp_f32_e32 v163, v163
	v_pk_mul_f32 v[2:3], v[6:7], v[2:3]
	v_exp_f32_e32 v166, v166
	v_exp_f32_e32 v167, v167
	v_pk_mul_f32 v[4:5], v[8:9], v[4:5]
	v_pk_add_f32 v[158:159], v[158:159], v[178:179]
	v_pk_add_f32 v[160:161], v[160:161], v[178:179]
	v_pk_add_f32 v[162:163], v[162:163], v[178:179]
	v_pk_add_f32 v[166:167], v[166:167], v[178:179]
	v_rcp_f32_e32 v158, v158
	v_rcp_f32_e32 v159, v159
	v_pk_mul_f32 v[10:11], v[10:11], v[172:173] op_sel_hi:[1,0]
	v_rcp_f32_e32 v160, v160
	v_rcp_f32_e32 v161, v161
	v_pk_mul_f32 v[12:13], v[12:13], v[172:173] op_sel_hi:[1,0]
	v_rcp_f32_e32 v162, v162
	v_rcp_f32_e32 v163, v163
	v_pk_mul_f32 v[2:3], v[2:3], v[172:173] op_sel_hi:[1,0]
	v_rcp_f32_e32 v166, v166
	v_rcp_f32_e32 v167, v167
	v_pk_mul_f32 v[4:5], v[4:5], v[172:173] op_sel_hi:[1,0]
	s_nop 0
	v_pk_mul_f32 v[10:11], v[10:11], v[158:159]
	v_pk_mul_f32 v[12:13], v[12:13], v[160:161]
	v_pk_mul_f32 v[2:3], v[2:3], v[162:163]
	v_pk_mul_f32 v[4:5], v[4:5], v[166:167]
	v_cvt_pk_bf16_f32 v132, v10, v11
	v_cvt_pk_bf16_f32 v133, v12, v13
	v_cvt_pk_bf16_f32 v134, v2, v3
	v_cvt_pk_bf16_f32 v135, v4, v5
	s_nop 0
	global_store_dwordx4 v131, v[132:135], s[40:41]
	s_andn2_b64 vcc, exec, s[38:39]
	s_nop 4
	s_mov_b64 s[40:41], -1
	s_cbranch_vccnz .LBB0_578
	s_andn2_b64 vcc, exec, s[2:3]
	s_cbranch_vccnz .LBB0_577
	s_barrier
	s_branch .LBB0_577
